# hoist rowss loads of rstd epilogues to unit header (no vmcnt(0) stall in gu/qkv epilogues) + relaxed first-iteration waits
# baseline (speedup 1.0000x reference)
; __device__ __forceinline__ float row_rstd(const float* __restrict__ rowss, int row) { const float ss = rowss[row]; return 1.0f / sqrtf(ss * (1.0f / 2048.0f) + 1e-6f); }
;     __host__ __device__ bool next(int i, Unit& u) const {
;         const long L = (long)i * G + c; if (L >= nwg) return false;
;         int wgid = (int)L; { const int q = nwg / NXCD, r = nwg % NXCD, xcd = wgid % NXCD, off = wgid / NXCD; wgid = (xcd < r ? xcd * (q + 1) : r * (q + 1) + (xcd - r) * q) + off; }
;         const int nig = WGM * nN, gid = wgid / nig, fm = gid * WGM, gsz = (nM - fm) < WGM ? (nM - fm) : WGM;
;         u.pm = fm + ((wgid % nig) % gsz); u.pn = (wgid % nig) / gsz; return true;
;     }
;     __device__ __forceinline__ void operator()(const f32x4 (&acc)[2][2][4][2], const Unit& u, int wr, int wc, int fr, int fq) const {
;     ...
;             for (int m = 0; m < 4; ++m) rsv[ai][m] = row_rstd(rowss, row0 + ai * HALF + m * 16);
.LBB0_746:
	v_lshl_add_u32 v0, s0, 8, v145
	v_ashrrev_i32_e32 v1, 31, v0
	v_lshl_add_u64 v[0:1], v[0:1], 2, s[18:19]
	global_load_dword v248, v[0:1], off
	global_load_dword v249, v[0:1], off offset:64
	global_load_dword v250, v[0:1], off offset:128
	global_load_dword v251, v[0:1], off offset:192
	global_load_dword v252, v[0:1], off offset:512
	global_load_dword v253, v[0:1], off offset:576
	global_load_dword v254, v[0:1], off offset:640
	global_load_dword v255, v[0:1], off offset:704
	s_add_i32 s41, s41, 1
	v_readlane_b32 s1, v247, 5
	s_mul_i32 s1, s41, s1
	s_mul_hi_u32 s6, s41, s33
	s_add_i32 s6, s6, s1
	s_mul_i32 s1, s41, s33
	s_add_u32 s10, s1, s82
	s_addc_u32 s11, s6, s3
	v_cmp_gt_i64_e32 vcc, s[10:11], v[142:143]
	v_cmp_lt_i64_e64 s[6:7], s[10:11], v[140:141]
	s_cbranch_vccnz .LBB0_748
	s_ashr_i32 s1, s10, 31
	s_lshr_b32 s1, s1, 29
	s_add_i32 s1, s10, s1
	s_ashr_i32 s11, s1, 3
	s_and_b32 s1, s1, -8
	s_sub_i32 s1, s10, s1
	s_cmp_lt_i32 s1, 0
	s_cselect_b32 s10, s36, 0x160
	s_mul_i32 s1, s10, s1
	s_add_i32 s1, s1, s11
	s_mul_hi_i32 s10, s1, 0x2e8ba2e9
	s_lshr_b32 s11, s10, 31
	s_ashr_i32 s10, s10, 6
	s_add_i32 s10, s10, s11
	s_lshl_b32 s11, s10, 3
	s_sub_i32 s24, 64, s11
	s_min_i32 s25, s24, 8
	s_abs_i32 s24, s25
	v_cvt_f32_u32_e32 v0, s24
	s_sub_i32 s27, 0, s24
	s_mulk_i32 s10, 0x160
	s_sub_i32 s1, s1, s10
	v_rcp_iflag_f32_e32 v0, v0
	s_abs_i32 s10, s1
	s_xor_b32 s26, s1, s25
	s_ashr_i32 s26, s26, 31
	v_mul_f32_e32 v0, 0x4f7ffffe, v0
	v_cvt_u32_f32_e32 v0, v0
	s_nop 0
	v_readfirstlane_b32 s28, v0
	s_mul_i32 s27, s27, s28
	s_mul_hi_u32 s27, s28, s27
	s_add_i32 s28, s28, s27
	s_mul_hi_u32 s27, s10, s28
	s_mul_i32 s28, s27, s24
	s_sub_i32 s10, s10, s28
	s_add_i32 s29, s27, 1
	s_sub_i32 s28, s10, s24
	s_cmp_ge_u32 s10, s24
	s_cselect_b32 s27, s29, s27
	s_cselect_b32 s10, s28, s10
	s_add_i32 s28, s27, 1
	s_cmp_ge_u32 s10, s24
	s_cselect_b32 s10, s28, s27
	s_xor_b32 s10, s10, s26
	s_sub_i32 s24, s10, s26
	s_mul_i32 s10, s24, s25
	s_sub_i32 s1, s1, s10
	s_add_i32 s26, s1, s11

; #define PG8_STAGE(bufoff, gbase, voff) do { _Pragma("unroll") for (int _i = 0; _i < 2; ++_i) \
;         __builtin_amdgcn_global_load_lds((const unsigned*)((const char*)(gbase) + (voff)[_i]), (PG8_LAS unsigned*)(lds + (bufoff) + ldsw + _i * 8192), 16, 0, 0); } while (0)
; #define PG8_LDA(dst, b, h) do { _Pragma("unroll") for (int m = 0; m < 4; ++m) _Pragma("unroll") for (int k = 0; k < 2; ++k) dst[m][k] = *(const PG8_LAS bf16x8*)(lds + PG8_SA(b, h) + aoff + m * 2048 + k * 1024); } while (0)
; #define PG8_LDB(dst, b, h) do { _Pragma("unroll") for (int n = 0; n < 2; ++n) _Pragma("unroll") for (int k = 0; k < 2; ++k) dst[n][k] = *(const PG8_LAS bf16x8*)(lds + PG8_SB(b, h) + boff + n * 2048 + k * 1024); } while (0)
; #define PG8_MMA(ai, bj, At, Bt) do { __builtin_amdgcn_s_setprio(1); _Pragma("unroll") for (int m = 0; m < 4; ++m) _Pragma("unroll") for (int n = 0; n < 2; ++n) _Pragma("unroll") for (int k = 0; k < 2; ++k) \
;         acc[ai][bj][m][n] = __builtin_amdgcn_mfma_f32_16x16x32_bf16(Bt[n][k], At[m][k], acc[ai][bj][m][n], 0, 0, 0); __builtin_amdgcn_s_setprio(0); } while (0)
; #define PG8_WAIT_V(n) asm volatile("s_waitcnt vmcnt(" #n ")" ::: "memory")
; #define PG8_WAIT_L(n) asm volatile("s_waitcnt lgkmcnt(" #n ")" ::: "memory")
; #define PG8_BAR __builtin_amdgcn_s_barrier()
; #define PG8_SCHED __builtin_amdgcn_sched_barrier(0)
; template <class Epi, class Sched, bool ALIGN_EPI = false, bool SP2 = false>
; __device__ __forceinline__ void gemm_phase(PG8_LAS unsigned char* lds, const Gemm g, const Sched& S, const Epi& E) {
;     ...
;             const bool last = (t == nt - 2);
;             const char* a1 = cA + (size_t)(t + 1) * kstep;
;             const char* a2 = last ? nA : cA + (size_t)(t + 2) * kstep; const char* b2 = last ? nB : cB + (size_t)(t + 2) * kstep;
;             const char* a3 = a2 + kstep; const char* b3 = b2 + kstep;
;             if (last && has_next) S.a_ready(nxt);
;             if constexpr (SP2) {
;             PG8_LDB(B0, 0, 0); PG8_LDB(B1, 0, 1); PG8_SCHED; PG8_LDA(At, 0, 0); PG8_STAGE(PG8_SA(1, 1), a1 + hstep, voffA);
;             PG8_WAIT_V(8); PG8_WAIT_L(0); PG8_BAR; PG8_MMA(0, 0, At, B0); PG8_MMA(0, 1, At, B1); PG8_BAR; PG8_SCHED;
.LBB0_749:
	ds_read_b128 v[146:149], v161
	ds_read_b128 v[150:153], v161 offset:1024
	ds_read_b128 v[170:173], v161 offset:2048
	ds_read_b128 v[174:177], v161 offset:3072
	ds_read_b128 v[178:181], v163
	ds_read_b128 v[182:185], v163 offset:1024
	ds_read_b128 v[186:189], v163 offset:2048
	ds_read_b128 v[190:193], v163 offset:3072
	s_add_u32 s10, s8, 0xfff80080
	s_addc_u32 s11, s9, -1
	s_cmp_eq_u32 s52, 28
	s_cselect_b32 s13, s1, s11
	s_cselect_b32 s12, s27, s10
	s_cselect_b32 s11, s25, s51
	s_cselect_b32 s10, s49, s50
	v_lshl_add_u64 v[156:157], s[8:9], 0, v[136:137]
	s_add_i32 m0, s37, 0xc000
	ds_read_b128 v[194:197], v165
	ds_read_b128 v[198:201], v165 offset:1024
	ds_read_b128 v[206:209], v165 offset:2048
	ds_read_b128 v[210:213], v165 offset:3072
	ds_read_b128 v[214:217], v165 offset:4096
	ds_read_b128 v[218:221], v165 offset:5120
	ds_read_b128 v[222:225], v165 offset:6144
	ds_read_b128 v[226:229], v165 offset:7168
	global_load_lds_dwordx4 v[156:157], off
	v_lshl_add_u64 v[156:157], s[8:9], 0, v[138:139]
	s_add_i32 m0, s37, 0xe000
	s_nop 0
	global_load_lds_dwordx4 v[156:157], off
	s_cmp_lg_u32 s52, -2
	s_cbranch_scc1 .Lgw_norm_749_0
	s_cmp_eq_u32 s41, 1
	s_cbranch_scc1 .Lgw_norm_749_0
	s_waitcnt vmcnt(24)
	s_branch .Lgw_join_749_0

; #define PG8_STAGE(bufoff, gbase, voff) do { _Pragma("unroll") for (int _i = 0; _i < 2; ++_i) \
;         __builtin_amdgcn_global_load_lds((const unsigned*)((const char*)(gbase) + (voff)[_i]), (PG8_LAS unsigned*)(lds + (bufoff) + ldsw + _i * 8192), 16, 0, 0); } while (0)
; #define PG8_LDA(dst, b, h) do { _Pragma("unroll") for (int m = 0; m < 4; ++m) _Pragma("unroll") for (int k = 0; k < 2; ++k) dst[m][k] = *(const PG8_LAS bf16x8*)(lds + PG8_SA(b, h) + aoff + m * 2048 + k * 1024); } while (0)
; #define PG8_MMA(ai, bj, At, Bt) do { __builtin_amdgcn_s_setprio(1); _Pragma("unroll") for (int m = 0; m < 4; ++m) _Pragma("unroll") for (int n = 0; n < 2; ++n) _Pragma("unroll") for (int k = 0; k < 2; ++k) \
;         acc[ai][bj][m][n] = __builtin_amdgcn_mfma_f32_16x16x32_bf16(Bt[n][k], At[m][k], acc[ai][bj][m][n], 0, 0, 0); __builtin_amdgcn_s_setprio(0); } while (0)
; #define PG8_WAIT_V(n) asm volatile("s_waitcnt vmcnt(" #n ")" ::: "memory")
; #define PG8_WAIT_L(n) asm volatile("s_waitcnt lgkmcnt(" #n ")" ::: "memory")
; #define PG8_BAR __builtin_amdgcn_s_barrier()
; #define PG8_SCHED __builtin_amdgcn_sched_barrier(0)
; template <class Epi, class Sched, bool ALIGN_EPI = false, bool SP2 = false>
; __device__ __forceinline__ void gemm_phase(PG8_LAS unsigned char* lds, const Gemm g, const Sched& S, const Epi& E) {
;     ...
;             PG8_WAIT_V(8); PG8_WAIT_L(0); PG8_BAR; PG8_MMA(0, 0, At, B0); PG8_MMA(0, 1, At, B1); PG8_BAR; PG8_SCHED;
;             PG8_LDA(At, 0, 1); PG8_STAGE(PG8_SB(0, 0), b2, voffB); PG8_STAGE(PG8_SB(0, 1), b2 + hstep, voffB); PG8_STAGE(PG8_SA(0, 0), a2, voffA);
;             PG8_WAIT_V(8); PG8_WAIT_L(0); PG8_BAR; PG8_MMA(1, 0, At, B0); PG8_MMA(1, 1, At, B1); PG8_BAR; PG8_SCHED;
.Lgw_join_749_0:
	s_waitcnt lgkmcnt(0)
	s_barrier
	s_setprio 1
	s_waitcnt lgkmcnt(0)
	v_mfma_f32_16x16x32_bf16 v[124:127], v[146:149], v[194:197], v[124:127]
	v_mfma_f32_16x16x32_bf16 v[120:123], v[170:173], v[194:197], v[120:123]
	v_mfma_f32_16x16x32_bf16 v[108:111], v[146:149], v[206:209], v[108:111]
	v_mfma_f32_16x16x32_bf16 v[104:107], v[170:173], v[206:209], v[104:107]
	v_mfma_f32_16x16x32_bf16 v[92:95], v[146:149], v[214:217], v[92:95]
	v_mfma_f32_16x16x32_bf16 v[88:91], v[170:173], v[214:217], v[88:91]
	v_mfma_f32_16x16x32_bf16 v[76:79], v[146:149], v[222:225], v[76:79]
	v_mfma_f32_16x16x32_bf16 v[72:75], v[170:173], v[222:225], v[72:75]
	v_mfma_f32_16x16x32_bf16 v[124:127], v[150:153], v[198:201], v[124:127]
	v_mfma_f32_16x16x32_bf16 v[120:123], v[174:177], v[198:201], v[120:123]
	v_mfma_f32_16x16x32_bf16 v[108:111], v[150:153], v[210:213], v[108:111]
	v_mfma_f32_16x16x32_bf16 v[104:107], v[174:177], v[210:213], v[104:107]
	v_mfma_f32_16x16x32_bf16 v[92:95], v[150:153], v[218:221], v[92:95]
	v_mfma_f32_16x16x32_bf16 v[88:91], v[174:177], v[218:221], v[88:91]
	v_mfma_f32_16x16x32_bf16 v[76:79], v[150:153], v[226:229], v[76:79]
	v_mfma_f32_16x16x32_bf16 v[72:75], v[174:177], v[226:229], v[72:75]
	s_setprio 0
	s_setprio 1
	v_mfma_f32_16x16x32_bf16 v[116:119], v[178:181], v[194:197], v[116:119]
	v_mfma_f32_16x16x32_bf16 v[112:115], v[186:189], v[194:197], v[112:115]
	v_mfma_f32_16x16x32_bf16 v[100:103], v[178:181], v[206:209], v[100:103]
	v_mfma_f32_16x16x32_bf16 v[96:99], v[186:189], v[206:209], v[96:99]
	v_mfma_f32_16x16x32_bf16 v[84:87], v[178:181], v[214:217], v[84:87]
	v_mfma_f32_16x16x32_bf16 v[80:83], v[186:189], v[214:217], v[80:83]
	v_mfma_f32_16x16x32_bf16 v[68:71], v[178:181], v[222:225], v[68:71]
	v_mfma_f32_16x16x32_bf16 v[64:67], v[186:189], v[222:225], v[64:67]
	v_mfma_f32_16x16x32_bf16 v[116:119], v[182:185], v[198:201], v[116:119]
	v_mfma_f32_16x16x32_bf16 v[112:115], v[190:193], v[198:201], v[112:115]
	v_mfma_f32_16x16x32_bf16 v[100:103], v[182:185], v[210:213], v[100:103]
	v_mfma_f32_16x16x32_bf16 v[96:99], v[190:193], v[210:213], v[96:99]
	v_mfma_f32_16x16x32_bf16 v[84:87], v[182:185], v[218:221], v[84:87]
	v_mfma_f32_16x16x32_bf16 v[80:83], v[190:193], v[218:221], v[80:83]
	v_mfma_f32_16x16x32_bf16 v[68:71], v[182:185], v[226:229], v[68:71]
	v_mfma_f32_16x16x32_bf16 v[64:67], v[190:193], v[226:229], v[64:67]
	s_setprio 0
	s_barrier
	s_add_i32 s53, s44, s35
	v_lshl_add_u64 v[156:157], s[10:11], 0, v[132:133]
	s_mov_b32 m0, s53
	ds_read_b128 v[194:197], v165 offset:16384
	ds_read_b128 v[198:201], v165 offset:17408
	ds_read_b128 v[206:209], v165 offset:18432
	ds_read_b128 v[210:213], v165 offset:19456
	ds_read_b128 v[214:217], v165 offset:20480
	ds_read_b128 v[218:221], v165 offset:21504
	ds_read_b128 v[222:225], v165 offset:22528
	ds_read_b128 v[226:229], v165 offset:23552
	global_load_lds_dwordx4 v[156:157], off
	s_add_i32 m0, s53, 0x2000
	s_add_u32 s54, s10, 0x80000
	v_lshl_add_u64 v[202:203], s[10:11], 0, v[128:129]
	s_addc_u32 s55, s11, 0
	s_add_i32 s53, s45, s35
	global_load_lds_dwordx4 v[202:203], off
	v_lshl_add_u64 v[230:231], s[54:55], 0, v[132:133]
	s_mov_b32 m0, s53
	v_lshl_add_u64 v[232:233], s[12:13], 0, v[130:131]
	global_load_lds_dwordx4 v[230:231], off
	v_lshl_add_u64 v[230:231], s[54:55], 0, v[128:129]
	s_add_i32 m0, s53, 0x2000
	s_nop 0
	global_load_lds_dwordx4 v[230:231], off
	v_lshl_add_u64 v[230:231], s[12:13], 0, v[134:135]
	s_mov_b32 m0, s37
	s_nop 0
	global_load_lds_dwordx4 v[230:231], off
	s_mov_b32 m0, s38
	s_nop 0
	global_load_lds_dwordx4 v[232:233], off
	s_cmp_lg_u32 s52, -2
	s_cbranch_scc1 .Lgw_norm_749_1
	s_cmp_eq_u32 s41, 1
	s_cbranch_scc1 .Lgw_norm_749_1
	s_waitcnt vmcnt(24)
	s_branch .Lgw_join_749_1

; __device__ __forceinline__ float row_rstd(const float* __restrict__ rowss, int row) { const float ss = rowss[row]; return 1.0f / sqrtf(ss * (1.0f / 2048.0f) + 1e-6f); }
;     __device__ __forceinline__ void operator()(const f32x4 (&acc)[2][2][4][2], const Unit& u, int wr, int wc, int fr, int fq) const {
;     ...
;         float rsv[2][4];
; #pragma unroll
;         for (int ai = 0; ai < 2; ++ai)
; #pragma unroll
;             for (int m = 0; m < 4; ++m) rsv[ai][m] = row_rstd(rowss, row0 + ai * HALF + m * 16);
.LBB0_752:
	v_lshl_add_u32 v150, s0, 8, v145
	v_ashrrev_i32_e32 v151, 31, v150
	v_lshl_add_u64 v[148:149], v[150:151], 2, s[18:19]
	v_mov_b32_e32 v144, v248
	v_or_b32_e32 v156, 16, v150
	v_ashrrev_i32_e32 v157, 31, v156
	v_or_b32_e32 v152, 32, v150
	v_or_b32_e32 v146, 48, v150
	v_lshl_add_u64 v[170:171], v[156:157], 2, s[18:19]
	v_ashrrev_i32_e32 v153, 31, v152
	v_ashrrev_i32_e32 v147, 31, v146
	v_lshl_add_u64 v[172:173], v[152:153], 2, s[18:19]
	v_lshl_add_u64 v[174:175], v[146:147], 2, s[18:19]
	v_mov_b32_e32 v147, v249
	v_mov_b32_e32 v151, v250
	v_mov_b32_e32 v153, v251
	v_mov_b32_e32 v154, v252
	v_mov_b32_e32 v157, v253
	v_mov_b32_e32 v158, v254
	s_nop 0
	v_mov_b32_e32 v148, v255
	s_nop 0
	v_fmamk_f32 v144, v144, 0x3a000000, v167
	v_mul_f32_e32 v149, 0x4f800000, v144
	v_cmp_gt_f32_e32 vcc, s46, v144
	v_fmamk_f32 v147, v147, 0x3a000000, v167
	s_nop 0
	v_cndmask_b32_e32 v144, v144, v149, vcc
	v_fmamk_f32 v151, v151, 0x3a000000, v167
	v_fmamk_f32 v153, v153, 0x3a000000, v167
	v_mul_f32_e32 v149, 0x4f800000, v147
	v_sqrt_f32_e32 v164, v144
	v_cmp_gt_f32_e64 s[0:1], s46, v147
	v_mul_f32_e32 v160, 0x4f800000, v151
	v_mul_f32_e32 v162, 0x4f800000, v153
	v_cndmask_b32_e64 v147, v147, v149, s[0:1]
	v_cmp_gt_f32_e64 s[8:9], s46, v151
	v_cmp_gt_f32_e64 s[10:11], s46, v153
	v_add_u32_e32 v166, 1, v164
	v_cndmask_b32_e64 v149, v151, v160, s[8:9]
	v_cndmask_b32_e64 v151, v153, v162, s[10:11]
	v_sqrt_f32_e32 v153, v147
	v_sqrt_f32_e32 v160, v149
	v_add_u32_e32 v162, -1, v164
	v_fma_f32 v169, -v162, v164, v144
	v_fma_f32 v170, -v166, v164, v144
	v_add_u32_e32 v171, -1, v153
	v_cmp_ge_f32_e64 s[12:13], 0, v169
	v_add_u32_e32 v173, -1, v160
	v_add_u32_e32 v172, 1, v153
	v_cndmask_b32_e64 v162, v164, v162, s[12:13]
	v_fma_f32 v164, -v171, v153, v147
	v_cmp_lt_f32_e64 s[12:13], 0, v170
	v_fma_f32 v175, -v173, v160, v149
	v_add_u32_e32 v174, 1, v160
	v_cndmask_b32_e64 v162, v162, v166, s[12:13]
	v_cmp_ge_f32_e64 s[12:13], 0, v164
	v_fma_f32 v169, -v172, v153, v147
	v_fma_f32 v176, -v174, v160, v149
	v_cndmask_b32_e64 v153, v153, v171, s[12:13]
	v_cmp_ge_f32_e64 s[12:13], 0, v175
	v_mul_f32_e32 v164, 0x37800000, v162
	v_cndmask_b32_e32 v162, v162, v164, vcc
	v_cndmask_b32_e64 v160, v160, v173, s[12:13]
	v_cmp_lt_f32_e64 s[12:13], 0, v169
	v_cmp_class_f32_e32 vcc, v144, v168
	v_fmamk_f32 v154, v154, 0x3a000000, v167
	v_cndmask_b32_e64 v153, v153, v172, s[12:13]
	v_cmp_lt_f32_e64 s[12:13], 0, v176
	v_mul_f32_e32 v164, 0x37800000, v153
	v_cndmask_b32_e32 v144, v162, v144, vcc
	v_cndmask_b32_e64 v160, v160, v174, s[12:13]
	v_cndmask_b32_e64 v153, v153, v164, s[0:1]
	v_div_scale_f32 v162, s[0:1], v144, v144, 1.0
	v_mul_f32_e32 v166, 0x37800000, v160
	v_cmp_class_f32_e64 s[0:1], v147, v168
	v_cndmask_b32_e64 v160, v160, v166, s[8:9]
	v_div_scale_f32 v164, vcc, 1.0, v144, 1.0
	v_cndmask_b32_e64 v147, v153, v147, s[0:1]
	v_cmp_class_f32_e64 s[0:1], v149, v168
	v_rcp_f32_e32 v153, v162
	v_fmamk_f32 v148, v148, 0x3a000000, v167
	v_cndmask_b32_e64 v149, v160, v149, s[0:1]
	v_div_scale_f32 v160, s[0:1], v147, v147, 1.0
	v_div_scale_f32 v169, s[8:9], v149, v149, 1.0
	v_rcp_f32_e32 v172, v160
	v_rcp_f32_e32 v173, v169
	v_fma_f32 v170, -v162, v153, 1.0
	v_fmac_f32_e32 v153, v170, v153
	v_fma_f32 v170, -v160, v172, 1.0
	v_div_scale_f32 v166, s[0:1], 1.0, v147, 1.0
	v_fma_f32 v174, -v169, v173, 1.0
	v_mul_f32_e32 v175, v164, v153
	v_fmac_f32_e32 v172, v170, v172
	v_fmac_f32_e32 v173, v174, v173
	v_fma_f32 v170, -v162, v175, v164
	v_mul_f32_e32 v174, v166, v172
	v_fmac_f32_e32 v175, v170, v153
	v_fma_f32 v170, -v160, v174, v166
	v_fma_f32 v162, -v162, v175, v164
	v_fmac_f32_e32 v174, v170, v172
	v_div_fmas_f32 v153, v162, v153, v175
	v_fma_f32 v160, -v160, v174, v166
	s_mov_b64 vcc, s[0:1]
	v_div_fixup_f32 v170, v153, v144, 1.0
	v_div_fmas_f32 v144, v160, v172, v174
	v_div_fixup_f32 v166, v144, v147, 1.0
	v_sqrt_f32_e32 v144, v151
	v_div_scale_f32 v171, s[8:9], 1.0, v149, 1.0
	v_mul_f32_e32 v176, v171, v173
	v_add_u32_e32 v153, -1, v144
	v_fma_f32 v160, -v153, v144, v151
	v_cmp_ge_f32_e32 vcc, 0, v160
	v_add_u32_e32 v160, 1, v144
	v_fma_f32 v147, -v169, v176, v171
	v_cndmask_b32_e32 v153, v144, v153, vcc
	v_fma_f32 v144, -v160, v144, v151
	v_cmp_lt_f32_e32 vcc, 0, v144
	v_fmac_f32_e32 v176, v147, v173
	v_fma_f32 v147, -v169, v176, v171
	v_cndmask_b32_e32 v144, v153, v160, vcc
	v_mul_f32_e32 v153, 0x37800000, v144
	v_cndmask_b32_e64 v144, v144, v153, s[10:11]
	v_cmp_class_f32_e32 vcc, v151, v168
	v_mul_f32_e32 v160, 0x4f800000, v154
	v_add_u32_e32 v169, 0x80, v150
	v_cndmask_b32_e32 v144, v144, v151, vcc
	v_div_scale_f32 v151, s[0:1], v144, v144, 1.0
	v_rcp_f32_e32 v153, v151
	s_mov_b64 vcc, s[8:9]
	v_div_fmas_f32 v147, v147, v173, v176
	v_cmp_gt_f32_e64 s[0:1], s46, v154
	v_div_fixup_f32 v164, v147, v149, 1.0
	v_fma_f32 v147, -v151, v153, 1.0
	v_cndmask_b32_e64 v154, v154, v160, s[0:1]
	v_fmac_f32_e32 v153, v147, v153
	v_div_scale_f32 v147, vcc, 1.0, v144, 1.0
	v_sqrt_f32_e32 v160, v154
	v_mul_f32_e32 v149, v147, v153
	v_fma_f32 v162, -v151, v149, v147
	v_fmac_f32_e32 v149, v162, v153
	v_fma_f32 v147, -v151, v149, v147
	v_add_u32_e32 v151, -1, v160
	v_fma_f32 v162, -v151, v160, v154
	v_cmp_ge_f32_e64 s[8:9], 0, v162
	v_add_u32_e32 v162, 1, v160
	v_div_fmas_f32 v147, v147, v153, v149
	v_cndmask_b32_e64 v151, v160, v151, s[8:9]
	v_fma_f32 v160, -v162, v160, v154
	v_cmp_lt_f32_e64 s[8:9], 0, v160
	v_fmamk_f32 v149, v157, 0x3a000000, v167
	v_mul_f32_e32 v153, 0x4f800000, v149
	v_cndmask_b32_e64 v151, v151, v162, s[8:9]
	v_mul_f32_e32 v160, 0x37800000, v151
	v_cndmask_b32_e64 v151, v151, v160, s[0:1]
	v_cmp_class_f32_e64 s[0:1], v154, v168
	v_div_fixup_f32 v162, v147, v144, 1.0
; __device__ __forceinline__ unsigned cvt_pk_bf16(float lo, float hi) { typedef float f2_t __attribute__((ext_vector_type(2))); typedef __bf16 b2_t __attribute__((ext_vector_type(2))); f2_t v = {lo, hi}; b2_t b = __builtin_convertvector(v, b2_t); return __builtin_bit_cast(unsigned, b); }
;     static __device__ __forceinline__ float sw(float g, float u) { return g * __builtin_amdgcn_rcpf(1.0f + __expf(-g)) * u; }
; __device__ __forceinline__ float row_rstd(const float* __restrict__ rowss, int row) { const float ss = rowss[row]; return 1.0f / sqrtf(ss * (1.0f / 2048.0f) + 1e-6f); }
;     static __device__ __forceinline__ float sw(float g, float u) { return g * __builtin_amdgcn_rcpf(1.0f + __expf(-g)) * u; }
;     __device__ __forceinline__ void operator()(const f32x4 (&acc)[2][2][4][2], const Unit& u, int wr, int wc, int fr, int fq) const {
;     ...
;             for (int m = 0; m < 4; ++m) rsv[ai][m] = row_rstd(rowss, row0 + ai * HALF + m * 16);
; #pragma unroll
;         for (int ai = 0; ai < 2; ++ai)
; #pragma unroll
;             for (int m = 0; m < 4; ++m) { const int row = row0 + ai * HALF + m * 16; const float rs = rsv[ai][m]; bf16_t* rowp = O + (size_t)row * ldc + col0;
;                 const f32x4 g0 = acc[ai][0][m][0] * rs, g1 = acc[ai][0][m][1] * rs, u0 = acc[ai][1][m][0] * rs, u1 = acc[ai][1][m][1] * rs;
;                 u32x4 w; w.x = cvt_pk_bf16(sw(g0[0], u0[0]), sw(g0[1], u0[1])); w.y = cvt_pk_bf16(sw(g0[2], u0[2]), sw(g0[3], u0[3]));
;                 w.z = cvt_pk_bf16(sw(g1[0], u1[0]), sw(g1[1], u1[1])); w.w = cvt_pk_bf16(sw(g1[2], u1[2]), sw(g1[3], u1[3]));
;                 *(u32x4*)rowp = w; }
	v_pk_mul_f32 v[108:109], v[108:109], v[166:167] op_sel_hi:[1,0]
	v_cndmask_b32_e64 v151, v151, v154, s[0:1]
	v_div_scale_f32 v154, s[0:1], v151, v151, 1.0
	v_rcp_f32_e32 v160, v154
	v_cmp_gt_f32_e64 s[0:1], s46, v149
	v_pk_mul_f32 v[110:111], v[110:111], v[166:167] op_sel_hi:[1,0]
	v_pk_mul_f32 v[100:101], v[100:101], v[166:167] op_sel_hi:[1,0]
	v_fma_f32 v144, -v154, v160, 1.0
	v_cndmask_b32_e64 v149, v149, v153, s[0:1]
	v_fmac_f32_e32 v160, v144, v160
	v_div_scale_f32 v144, vcc, 1.0, v151, 1.0
	v_sqrt_f32_e32 v153, v149
	v_mul_f32_e32 v147, v144, v160
	v_fma_f32 v157, -v154, v147, v144
	v_fmac_f32_e32 v147, v157, v160
	v_fma_f32 v144, -v154, v147, v144
	v_add_u32_e32 v154, -1, v153
	v_fma_f32 v157, -v154, v153, v149
	v_cmp_ge_f32_e64 s[8:9], 0, v157
	v_add_u32_e32 v157, 1, v153
	v_div_fmas_f32 v144, v144, v160, v147
	v_cndmask_b32_e64 v154, v153, v154, s[8:9]
	v_fma_f32 v153, -v157, v153, v149
	v_cmp_lt_f32_e64 s[8:9], 0, v153
	v_div_fixup_f32 v160, v144, v151, 1.0
	v_fmamk_f32 v151, v158, 0x3a000000, v167
	v_cndmask_b32_e64 v153, v154, v157, s[8:9]
	v_mul_f32_e32 v154, 0x37800000, v153
	v_cndmask_b32_e64 v153, v153, v154, s[0:1]
	v_cmp_class_f32_e64 s[0:1], v149, v168
	v_mul_f32_e32 v158, 0x4f800000, v151
	v_add_u32_e32 v157, 0x90, v150
	v_cndmask_b32_e64 v149, v153, v149, s[0:1]
	v_div_scale_f32 v153, s[0:1], v149, v149, 1.0
	v_rcp_f32_e32 v154, v153
	v_cmp_gt_f32_e64 s[0:1], s46, v151
	v_pk_mul_f32 v[104:105], v[104:105], v[166:167] op_sel_hi:[1,0]
	v_pk_mul_f32 v[102:103], v[102:103], v[166:167] op_sel_hi:[1,0]
	v_fma_f32 v144, -v153, v154, 1.0
	v_cndmask_b32_e64 v151, v151, v158, s[0:1]
	v_fmac_f32_e32 v154, v144, v154
	v_div_scale_f32 v144, vcc, 1.0, v149, 1.0
	v_sqrt_f32_e32 v158, v151
	v_mul_f32_e32 v147, v144, v154
	v_fma_f32 v171, -v153, v147, v144
	v_fmac_f32_e32 v147, v171, v154
	v_fma_f32 v144, -v153, v147, v144
	v_add_u32_e32 v153, -1, v158
	v_fma_f32 v171, -v153, v158, v151
	v_cmp_ge_f32_e64 s[8:9], 0, v171
	v_add_u32_e32 v171, 1, v158
	v_div_fmas_f32 v144, v144, v154, v147
	v_cndmask_b32_e64 v153, v158, v153, s[8:9]
	v_fma_f32 v158, -v171, v158, v151
	v_cmp_lt_f32_e64 s[8:9], 0, v158
	v_pk_mul_f32 v[106:107], v[106:107], v[166:167] op_sel_hi:[1,0]
	v_pk_mul_f32 v[92:93], v[92:93], v[164:165] op_sel_hi:[1,0]
	v_cndmask_b32_e64 v153, v153, v171, s[8:9]
	v_mul_f32_e32 v158, 0x37800000, v153
	v_cndmask_b32_e64 v153, v153, v158, s[0:1]
	v_cmp_class_f32_e64 s[0:1], v151, v168
	v_div_fixup_f32 v158, v144, v149, 1.0
	v_mul_f32_e32 v149, 0x4f800000, v148
	v_cndmask_b32_e64 v151, v153, v151, s[0:1]
	v_div_scale_f32 v171, s[0:1], v151, v151, 1.0
	v_rcp_f32_e32 v172, v171
	v_cmp_gt_f32_e64 s[0:1], s46, v148
	v_add_u32_e32 v153, 0xa0, v150
	v_pk_mul_f32 v[94:95], v[94:95], v[164:165] op_sel_hi:[1,0]
	v_cndmask_b32_e64 v148, v148, v149, s[0:1]
	v_fma_f32 v144, -v171, v172, 1.0
	v_sqrt_f32_e32 v149, v148
	v_fmac_f32_e32 v172, v144, v172
	v_div_scale_f32 v144, vcc, 1.0, v151, 1.0
	v_mul_f32_e32 v147, v144, v172
	v_fma_f32 v154, -v171, v147, v144
	v_fmac_f32_e32 v147, v154, v172
	v_add_u32_e32 v154, -1, v149
	v_fma_f32 v144, -v171, v147, v144
	v_fma_f32 v171, -v154, v149, v148
	v_cmp_ge_f32_e64 s[8:9], 0, v171
	v_add_u32_e32 v171, 1, v149
	v_div_fmas_f32 v144, v144, v172, v147
	v_cndmask_b32_e64 v154, v149, v154, s[8:9]
	v_fma_f32 v149, -v171, v149, v148
	v_cmp_lt_f32_e64 s[8:9], 0, v149
	v_add_u32_e32 v147, 0xb0, v150
	v_pk_mul_f32 v[84:85], v[84:85], v[164:165] op_sel_hi:[1,0]
	v_cndmask_b32_e64 v149, v154, v171, s[8:9]
	v_mul_f32_e32 v154, 0x37800000, v149
	v_cndmask_b32_e64 v149, v149, v154, s[0:1]
	v_cmp_class_f32_e64 s[0:1], v148, v168
	v_div_fixup_f32 v154, v144, v151, 1.0
	v_pk_mul_f32 v[88:89], v[88:89], v[164:165] op_sel_hi:[1,0]
	v_cndmask_b32_e64 v148, v149, v148, s[0:1]
	v_div_scale_f32 v149, s[0:1], v148, v148, 1.0
	v_rcp_f32_e32 v171, v149
	v_pk_mul_f32 v[86:87], v[86:87], v[164:165] op_sel_hi:[1,0]
	v_pk_mul_f32 v[90:91], v[90:91], v[164:165] op_sel_hi:[1,0]
	v_pk_mul_f32 v[76:77], v[76:77], v[162:163] op_sel_hi:[1,0]
	v_fma_f32 v144, -v149, v171, 1.0
	v_fmac_f32_e32 v171, v144, v171
	v_div_scale_f32 v144, vcc, 1.0, v148, 1.0
	v_mul_f32_e32 v151, v144, v171
	v_fma_f32 v172, -v149, v151, v144
	v_fmac_f32_e32 v151, v172, v171
	v_fma_f32 v144, -v149, v151, v144
	v_div_fmas_f32 v144, v144, v171, v151
	v_lshl_or_b32 v172, s48, 7, v159
	v_div_fixup_f32 v144, v144, v148, 1.0
	v_ashrrev_i32_e32 v173, 31, v172
	v_mov_b64_e32 v[148:149], s[16:17]
	v_mad_i64_i32 v[174:175], s[0:1], v150, s47, v[148:149]
	v_lshlrev_b64 v[150:151], 1, v[172:173]
	v_pk_mul_f32 v[124:125], v[124:125], v[170:171] op_sel_hi:[1,0]
	v_lshl_add_u64 v[172:173], v[174:175], 0, v[150:151]
	v_pk_mul_f32 v[174:175], v[114:115], v[170:171] op_sel_hi:[1,0]
	v_mul_f32_e32 v114, 0xbfb8aa3b, v124
	v_pk_mul_f32 v[126:127], v[126:127], v[170:171] op_sel_hi:[1,0]
	v_pk_mul_f32 v[122:123], v[122:123], v[170:171] op_sel_hi:[1,0]
	v_pk_mul_f32 v[120:121], v[120:121], v[170:171] op_sel_hi:[1,0]
	v_pk_mul_f32 v[118:119], v[118:119], v[170:171] op_sel_hi:[1,0]
	v_pk_mul_f32 v[116:117], v[116:117], v[170:171] op_sel_hi:[1,0]
	v_exp_f32_e32 v171, v114
	v_mul_f32_e32 v114, 0xbfb8aa3b, v125
	v_exp_f32_e32 v176, v114
	v_pk_mul_f32 v[78:79], v[78:79], v[162:163] op_sel_hi:[1,0]
	v_pk_mul_f32 v[114:115], v[112:113], v[170:171] op_sel_hi:[1,0]
	v_add_f32_e32 v112, 1.0, v171
	v_mul_f32_e32 v170, 0xbfb8aa3b, v126
	v_mul_f32_e32 v171, 0xbfb8aa3b, v127
	v_exp_f32_e32 v170, v170
	v_exp_f32_e32 v171, v171
	v_add_f32_e32 v113, 1.0, v176
	v_rcp_f32_e32 v112, v112
	v_rcp_f32_e32 v113, v113
	v_add_f32_e32 v170, 1.0, v170
	v_add_f32_e32 v171, 1.0, v171
	v_rcp_f32_e32 v170, v170
; __device__ __forceinline__ unsigned cvt_pk_bf16(float lo, float hi) { typedef float f2_t __attribute__((ext_vector_type(2))); typedef __bf16 b2_t __attribute__((ext_vector_type(2))); f2_t v = {lo, hi}; b2_t b = __builtin_convertvector(v, b2_t); return __builtin_bit_cast(unsigned, b); }
;     static __device__ __forceinline__ float sw(float g, float u) { return g * __builtin_amdgcn_rcpf(1.0f + __expf(-g)) * u; }
;     static __device__ __forceinline__ float sw(float g, float u) { return g * __builtin_amdgcn_rcpf(1.0f + __expf(-g)) * u; }
;     __device__ __forceinline__ void operator()(const f32x4 (&acc)[2][2][4][2], const Unit& u, int wr, int wc, int fr, int fq) const {
;     ...
;         for (int ai = 0; ai < 2; ++ai)
; #pragma unroll
;             for (int m = 0; m < 4; ++m) { const int row = row0 + ai * HALF + m * 16; const float rs = rsv[ai][m]; bf16_t* rowp = O + (size_t)row * ldc + col0;
;                 const f32x4 g0 = acc[ai][0][m][0] * rs, g1 = acc[ai][0][m][1] * rs, u0 = acc[ai][1][m][0] * rs, u1 = acc[ai][1][m][1] * rs;
;                 u32x4 w; w.x = cvt_pk_bf16(sw(g0[0], u0[0]), sw(g0[1], u0[1])); w.y = cvt_pk_bf16(sw(g0[2], u0[2]), sw(g0[3], u0[3]));
;                 w.z = cvt_pk_bf16(sw(g1[0], u1[0]), sw(g1[1], u1[1])); w.w = cvt_pk_bf16(sw(g1[2], u1[2]), sw(g1[3], u1[3]));
;                 *(u32x4*)rowp = w; }
	v_rcp_f32_e32 v171, v171
	v_pk_mul_f32 v[112:113], v[124:125], v[112:113]
	v_pk_mul_f32 v[68:69], v[68:69], v[162:163] op_sel_hi:[1,0]
	v_pk_mul_f32 v[112:113], v[116:117], v[112:113]
	v_pk_mul_f32 v[116:117], v[126:127], v[170:171]
	v_cvt_pk_bf16_f32 v112, v112, v113
	v_mul_f32_e32 v113, 0xbfb8aa3b, v120
	v_pk_mul_f32 v[116:117], v[118:119], v[116:117]
	v_exp_f32_e32 v118, v113
	v_mul_f32_e32 v113, 0xbfb8aa3b, v121
	v_exp_f32_e32 v119, v113
	v_cvt_pk_bf16_f32 v113, v116, v117
	v_add_f32_e32 v116, 1.0, v118
	v_mul_f32_e32 v118, 0xbfb8aa3b, v122
	v_add_f32_e32 v117, 1.0, v119
	v_mul_f32_e32 v119, 0xbfb8aa3b, v123
	v_exp_f32_e32 v118, v118
	v_exp_f32_e32 v119, v119
	v_rcp_f32_e32 v116, v116
	v_rcp_f32_e32 v117, v117
	v_add_f32_e32 v118, 1.0, v118
	v_add_f32_e32 v119, 1.0, v119
	v_rcp_f32_e32 v118, v118
	v_rcp_f32_e32 v119, v119
	v_pk_mul_f32 v[116:117], v[120:121], v[116:117]
	v_pk_mul_f32 v[72:73], v[72:73], v[162:163] op_sel_hi:[1,0]
	v_pk_mul_f32 v[114:115], v[114:115], v[116:117]
	v_pk_mul_f32 v[116:117], v[122:123], v[118:119]
	v_cvt_pk_bf16_f32 v114, v114, v115
	v_pk_mul_f32 v[116:117], v[174:175], v[116:117]
	v_pk_mul_f32 v[70:71], v[70:71], v[162:163] op_sel_hi:[1,0]
	v_cvt_pk_bf16_f32 v115, v116, v117
	global_store_dwordx4 v[172:173], v[112:115], off
	v_pk_mul_f32 v[74:75], v[74:75], v[162:163] op_sel_hi:[1,0]
	v_pk_mul_f32 v[60:61], v[60:61], v[160:161] op_sel_hi:[1,0]
	v_pk_mul_f32 v[114:115], v[98:99], v[166:167] op_sel_hi:[1,0]
	v_mul_f32_e32 v98, 0xbfb8aa3b, v108
	v_exp_f32_e32 v116, v98
	v_mul_f32_e32 v98, 0xbfb8aa3b, v109
	v_exp_f32_e32 v117, v98
	v_pk_mul_f32 v[98:99], v[96:97], v[166:167] op_sel_hi:[1,0]
	v_add_f32_e32 v96, 1.0, v116
	v_mul_f32_e32 v116, 0xbfb8aa3b, v110
	v_add_f32_e32 v97, 1.0, v117
	v_mul_f32_e32 v117, 0xbfb8aa3b, v111
	v_exp_f32_e32 v116, v116
	v_exp_f32_e32 v117, v117
	v_rcp_f32_e32 v96, v96
	v_rcp_f32_e32 v97, v97
	v_add_f32_e32 v116, 1.0, v116
	v_add_f32_e32 v117, 1.0, v117
	v_rcp_f32_e32 v116, v116
	v_rcp_f32_e32 v117, v117
	v_pk_mul_f32 v[96:97], v[108:109], v[96:97]
	v_mad_i64_i32 v[112:113], s[0:1], v156, s47, v[148:149]
	v_pk_mul_f32 v[96:97], v[100:101], v[96:97]
	v_pk_mul_f32 v[100:101], v[110:111], v[116:117]
	v_cvt_pk_bf16_f32 v96, v96, v97
	v_mul_f32_e32 v97, 0xbfb8aa3b, v104
	v_pk_mul_f32 v[100:101], v[102:103], v[100:101]
	v_exp_f32_e32 v102, v97
	v_mul_f32_e32 v97, 0xbfb8aa3b, v105
	v_exp_f32_e32 v103, v97
	v_cvt_pk_bf16_f32 v97, v100, v101
	v_add_f32_e32 v100, 1.0, v102
	v_mul_f32_e32 v102, 0xbfb8aa3b, v106
	v_add_f32_e32 v101, 1.0, v103
	v_mul_f32_e32 v103, 0xbfb8aa3b, v107
	v_exp_f32_e32 v102, v102
	v_exp_f32_e32 v103, v103
	v_rcp_f32_e32 v100, v100
	v_rcp_f32_e32 v101, v101
	v_add_f32_e32 v102, 1.0, v102
	v_add_f32_e32 v103, 1.0, v103
	v_rcp_f32_e32 v102, v102
	v_rcp_f32_e32 v103, v103
	v_pk_mul_f32 v[100:101], v[104:105], v[100:101]
	v_lshl_add_u64 v[112:113], v[112:113], 0, v[150:151]
	v_pk_mul_f32 v[98:99], v[98:99], v[100:101]
	v_pk_mul_f32 v[100:101], v[106:107], v[102:103]
	v_cvt_pk_bf16_f32 v98, v98, v99
	v_pk_mul_f32 v[100:101], v[114:115], v[100:101]
	v_pk_mul_f32 v[62:63], v[62:63], v[160:161] op_sel_hi:[1,0]
	v_cvt_pk_bf16_f32 v99, v100, v101
	global_store_dwordx4 v[112:113], v[96:99], off
	v_pk_mul_f32 v[52:53], v[52:53], v[160:161] op_sel_hi:[1,0]
	v_pk_mul_f32 v[56:57], v[56:57], v[160:161] op_sel_hi:[1,0]
	v_pk_mul_f32 v[98:99], v[82:83], v[164:165] op_sel_hi:[1,0]
	v_mul_f32_e32 v82, 0xbfb8aa3b, v92
	v_exp_f32_e32 v100, v82
	v_mul_f32_e32 v82, 0xbfb8aa3b, v93
	v_exp_f32_e32 v101, v82
	v_pk_mul_f32 v[82:83], v[80:81], v[164:165] op_sel_hi:[1,0]
	v_add_f32_e32 v80, 1.0, v100
	v_mul_f32_e32 v100, 0xbfb8aa3b, v94
	v_add_f32_e32 v81, 1.0, v101
	v_mul_f32_e32 v101, 0xbfb8aa3b, v95
	v_exp_f32_e32 v100, v100
	v_exp_f32_e32 v101, v101
	v_rcp_f32_e32 v80, v80
	v_rcp_f32_e32 v81, v81
	v_add_f32_e32 v100, 1.0, v100
	v_add_f32_e32 v101, 1.0, v101
	v_rcp_f32_e32 v100, v100
	v_rcp_f32_e32 v101, v101
	v_pk_mul_f32 v[80:81], v[92:93], v[80:81]
	v_mad_i64_i32 v[96:97], s[0:1], v152, s47, v[148:149]
	v_pk_mul_f32 v[80:81], v[84:85], v[80:81]
	v_pk_mul_f32 v[84:85], v[94:95], v[100:101]
	v_cvt_pk_bf16_f32 v80, v80, v81
	v_mul_f32_e32 v81, 0xbfb8aa3b, v88
	v_pk_mul_f32 v[84:85], v[86:87], v[84:85]
	v_exp_f32_e32 v86, v81
	v_mul_f32_e32 v81, 0xbfb8aa3b, v89
	v_exp_f32_e32 v87, v81
	v_cvt_pk_bf16_f32 v81, v84, v85
	v_add_f32_e32 v84, 1.0, v86
	v_mul_f32_e32 v86, 0xbfb8aa3b, v90
	v_add_f32_e32 v85, 1.0, v87
	v_mul_f32_e32 v87, 0xbfb8aa3b, v91
	v_exp_f32_e32 v86, v86
	v_exp_f32_e32 v87, v87
	v_rcp_f32_e32 v84, v84
	v_rcp_f32_e32 v85, v85
	v_add_f32_e32 v86, 1.0, v86
	v_add_f32_e32 v87, 1.0, v87
	v_rcp_f32_e32 v86, v86
	v_rcp_f32_e32 v87, v87
	v_pk_mul_f32 v[84:85], v[88:89], v[84:85]
	v_lshl_add_u64 v[96:97], v[96:97], 0, v[150:151]
	v_pk_mul_f32 v[82:83], v[82:83], v[84:85]
	v_pk_mul_f32 v[84:85], v[90:91], v[86:87]
	v_cvt_pk_bf16_f32 v82, v82, v83
	v_pk_mul_f32 v[84:85], v[98:99], v[84:85]
	v_pk_mul_f32 v[54:55], v[54:55], v[160:161] op_sel_hi:[1,0]
	v_cvt_pk_bf16_f32 v83, v84, v85
	global_store_dwordx4 v[96:97], v[80:83], off
	v_pk_mul_f32 v[58:59], v[58:59], v[160:161] op_sel_hi:[1,0]
	v_pk_mul_f32 v[44:45], v[44:45], v[158:159] op_sel_hi:[1,0]
	v_pk_mul_f32 v[82:83], v[66:67], v[162:163] op_sel_hi:[1,0]
	v_mul_f32_e32 v66, 0xbfb8aa3b, v76
	v_exp_f32_e32 v84, v66
	v_mul_f32_e32 v66, 0xbfb8aa3b, v77
	v_exp_f32_e32 v85, v66
	v_pk_mul_f32 v[66:67], v[64:65], v[162:163] op_sel_hi:[1,0]
	v_add_f32_e32 v64, 1.0, v84
	v_mul_f32_e32 v84, 0xbfb8aa3b, v78
	v_add_f32_e32 v65, 1.0, v85
	v_mul_f32_e32 v85, 0xbfb8aa3b, v79
	v_exp_f32_e32 v84, v84
	v_exp_f32_e32 v85, v85
	v_rcp_f32_e32 v64, v64
; __device__ __forceinline__ unsigned cvt_pk_bf16(float lo, float hi) { typedef float f2_t __attribute__((ext_vector_type(2))); typedef __bf16 b2_t __attribute__((ext_vector_type(2))); f2_t v = {lo, hi}; b2_t b = __builtin_convertvector(v, b2_t); return __builtin_bit_cast(unsigned, b); }
;     static __device__ __forceinline__ float sw(float g, float u) { return g * __builtin_amdgcn_rcpf(1.0f + __expf(-g)) * u; }
;     static __device__ __forceinline__ float sw(float g, float u) { return g * __builtin_amdgcn_rcpf(1.0f + __expf(-g)) * u; }
;     __device__ __forceinline__ void operator()(const f32x4 (&acc)[2][2][4][2], const Unit& u, int wr, int wc, int fr, int fq) const {
;     ...
;         for (int ai = 0; ai < 2; ++ai)
; #pragma unroll
;             for (int m = 0; m < 4; ++m) { const int row = row0 + ai * HALF + m * 16; const float rs = rsv[ai][m]; bf16_t* rowp = O + (size_t)row * ldc + col0;
;                 const f32x4 g0 = acc[ai][0][m][0] * rs, g1 = acc[ai][0][m][1] * rs, u0 = acc[ai][1][m][0] * rs, u1 = acc[ai][1][m][1] * rs;
;                 u32x4 w; w.x = cvt_pk_bf16(sw(g0[0], u0[0]), sw(g0[1], u0[1])); w.y = cvt_pk_bf16(sw(g0[2], u0[2]), sw(g0[3], u0[3]));
;                 w.z = cvt_pk_bf16(sw(g1[0], u1[0]), sw(g1[1], u1[1])); w.w = cvt_pk_bf16(sw(g1[2], u1[2]), sw(g1[3], u1[3]));
;                 *(u32x4*)rowp = w; }
	v_rcp_f32_e32 v65, v65
	v_add_f32_e32 v84, 1.0, v84
	v_add_f32_e32 v85, 1.0, v85
	v_rcp_f32_e32 v84, v84
	v_rcp_f32_e32 v85, v85
	v_pk_mul_f32 v[64:65], v[76:77], v[64:65]
	v_mad_i64_i32 v[80:81], s[0:1], v146, s47, v[148:149]
	v_pk_mul_f32 v[64:65], v[68:69], v[64:65]
	v_pk_mul_f32 v[68:69], v[78:79], v[84:85]
	v_cvt_pk_bf16_f32 v64, v64, v65
	v_mul_f32_e32 v65, 0xbfb8aa3b, v72
	v_pk_mul_f32 v[68:69], v[70:71], v[68:69]
	v_exp_f32_e32 v70, v65
	v_mul_f32_e32 v65, 0xbfb8aa3b, v73
	v_exp_f32_e32 v71, v65
	v_cvt_pk_bf16_f32 v65, v68, v69
	v_add_f32_e32 v68, 1.0, v70
	v_mul_f32_e32 v70, 0xbfb8aa3b, v74
	v_add_f32_e32 v69, 1.0, v71
	v_mul_f32_e32 v71, 0xbfb8aa3b, v75
	v_exp_f32_e32 v70, v70
	v_exp_f32_e32 v71, v71
	v_rcp_f32_e32 v68, v68
	v_rcp_f32_e32 v69, v69
	v_add_f32_e32 v70, 1.0, v70
	v_add_f32_e32 v71, 1.0, v71
	v_rcp_f32_e32 v70, v70
	v_rcp_f32_e32 v71, v71
	v_pk_mul_f32 v[68:69], v[72:73], v[68:69]
	v_lshl_add_u64 v[80:81], v[80:81], 0, v[150:151]
	v_pk_mul_f32 v[66:67], v[66:67], v[68:69]
	v_pk_mul_f32 v[68:69], v[74:75], v[70:71]
	v_cvt_pk_bf16_f32 v66, v66, v67
	v_pk_mul_f32 v[68:69], v[82:83], v[68:69]
	v_pk_mul_f32 v[46:47], v[46:47], v[158:159] op_sel_hi:[1,0]
	v_cvt_pk_bf16_f32 v67, v68, v69
	global_store_dwordx4 v[80:81], v[64:67], off
	v_pk_mul_f32 v[36:37], v[36:37], v[158:159] op_sel_hi:[1,0]
	v_pk_mul_f32 v[40:41], v[40:41], v[158:159] op_sel_hi:[1,0]
	v_pk_mul_f32 v[66:67], v[50:51], v[160:161] op_sel_hi:[1,0]
	v_mul_f32_e32 v50, 0xbfb8aa3b, v60
	v_exp_f32_e32 v68, v50
	v_mul_f32_e32 v50, 0xbfb8aa3b, v61
	v_exp_f32_e32 v69, v50
	v_pk_mul_f32 v[50:51], v[48:49], v[160:161] op_sel_hi:[1,0]
	v_add_f32_e32 v48, 1.0, v68
	v_mul_f32_e32 v68, 0xbfb8aa3b, v62
	v_add_f32_e32 v49, 1.0, v69
	v_mul_f32_e32 v69, 0xbfb8aa3b, v63
	v_exp_f32_e32 v68, v68
	v_exp_f32_e32 v69, v69
	v_rcp_f32_e32 v48, v48
	v_rcp_f32_e32 v49, v49
	v_add_f32_e32 v68, 1.0, v68
	v_add_f32_e32 v69, 1.0, v69
	v_rcp_f32_e32 v68, v68
	v_rcp_f32_e32 v69, v69
	v_pk_mul_f32 v[48:49], v[60:61], v[48:49]
	v_mad_i64_i32 v[64:65], s[0:1], v169, s47, v[148:149]
	v_pk_mul_f32 v[48:49], v[52:53], v[48:49]
	v_pk_mul_f32 v[52:53], v[62:63], v[68:69]
	v_cvt_pk_bf16_f32 v48, v48, v49
	v_mul_f32_e32 v49, 0xbfb8aa3b, v56
	v_pk_mul_f32 v[52:53], v[54:55], v[52:53]
	v_exp_f32_e32 v54, v49
	v_mul_f32_e32 v49, 0xbfb8aa3b, v57
	v_exp_f32_e32 v55, v49
	v_cvt_pk_bf16_f32 v49, v52, v53
	v_add_f32_e32 v52, 1.0, v54
	v_mul_f32_e32 v54, 0xbfb8aa3b, v58
	v_add_f32_e32 v53, 1.0, v55
	v_mul_f32_e32 v55, 0xbfb8aa3b, v59
	v_exp_f32_e32 v54, v54
	v_exp_f32_e32 v55, v55
	v_rcp_f32_e32 v52, v52
	v_rcp_f32_e32 v53, v53
	v_add_f32_e32 v54, 1.0, v54
	v_add_f32_e32 v55, 1.0, v55
	v_rcp_f32_e32 v54, v54
	v_rcp_f32_e32 v55, v55
	v_pk_mul_f32 v[52:53], v[56:57], v[52:53]
	v_lshl_add_u64 v[64:65], v[64:65], 0, v[150:151]
	v_pk_mul_f32 v[50:51], v[50:51], v[52:53]
	v_pk_mul_f32 v[52:53], v[58:59], v[54:55]
	v_cvt_pk_bf16_f32 v50, v50, v51
	v_pk_mul_f32 v[52:53], v[66:67], v[52:53]
	v_pk_mul_f32 v[38:39], v[38:39], v[158:159] op_sel_hi:[1,0]
	v_cvt_pk_bf16_f32 v51, v52, v53
	global_store_dwordx4 v[64:65], v[48:51], off
	v_pk_mul_f32 v[42:43], v[42:43], v[158:159] op_sel_hi:[1,0]
	v_pk_mul_f32 v[28:29], v[28:29], v[154:155] op_sel_hi:[1,0]
	v_pk_mul_f32 v[50:51], v[34:35], v[158:159] op_sel_hi:[1,0]
	v_mul_f32_e32 v34, 0xbfb8aa3b, v44
	v_exp_f32_e32 v52, v34
	v_mul_f32_e32 v34, 0xbfb8aa3b, v45
	v_exp_f32_e32 v53, v34
	v_pk_mul_f32 v[34:35], v[32:33], v[158:159] op_sel_hi:[1,0]
	v_add_f32_e32 v32, 1.0, v52
	v_mul_f32_e32 v52, 0xbfb8aa3b, v46
	v_add_f32_e32 v33, 1.0, v53
	v_mul_f32_e32 v53, 0xbfb8aa3b, v47
	v_exp_f32_e32 v52, v52
	v_exp_f32_e32 v53, v53
	v_rcp_f32_e32 v32, v32
	v_rcp_f32_e32 v33, v33
	v_add_f32_e32 v52, 1.0, v52
	v_add_f32_e32 v53, 1.0, v53
	v_rcp_f32_e32 v52, v52
	v_rcp_f32_e32 v53, v53
	v_pk_mul_f32 v[32:33], v[44:45], v[32:33]
	v_mad_i64_i32 v[48:49], s[0:1], v157, s47, v[148:149]
	v_pk_mul_f32 v[32:33], v[36:37], v[32:33]
	v_pk_mul_f32 v[36:37], v[46:47], v[52:53]
	v_cvt_pk_bf16_f32 v32, v32, v33
	v_mul_f32_e32 v33, 0xbfb8aa3b, v40
	v_pk_mul_f32 v[36:37], v[38:39], v[36:37]
	v_exp_f32_e32 v38, v33
	v_mul_f32_e32 v33, 0xbfb8aa3b, v41
	v_exp_f32_e32 v39, v33
	v_cvt_pk_bf16_f32 v33, v36, v37
	v_add_f32_e32 v36, 1.0, v38
	v_mul_f32_e32 v38, 0xbfb8aa3b, v42
	v_add_f32_e32 v37, 1.0, v39
	v_mul_f32_e32 v39, 0xbfb8aa3b, v43
	v_exp_f32_e32 v38, v38
	v_exp_f32_e32 v39, v39
	v_rcp_f32_e32 v36, v36
	v_rcp_f32_e32 v37, v37
	v_add_f32_e32 v38, 1.0, v38
; __device__ __forceinline__ unsigned cvt_pk_bf16(float lo, float hi) { typedef float f2_t __attribute__((ext_vector_type(2))); typedef __bf16 b2_t __attribute__((ext_vector_type(2))); f2_t v = {lo, hi}; b2_t b = __builtin_convertvector(v, b2_t); return __builtin_bit_cast(unsigned, b); }
;     static __device__ __forceinline__ float sw(float g, float u) { return g * __builtin_amdgcn_rcpf(1.0f + __expf(-g)) * u; }
;     static __device__ __forceinline__ float sw(float g, float u) { return g * __builtin_amdgcn_rcpf(1.0f + __expf(-g)) * u; }
; #define PG8_BAR __builtin_amdgcn_s_barrier()
;     __device__ __forceinline__ void operator()(const f32x4 (&acc)[2][2][4][2], const Unit& u, int wr, int wc, int fr, int fq) const {
;     ...
;         for (int ai = 0; ai < 2; ++ai)
; #pragma unroll
;             for (int m = 0; m < 4; ++m) { const int row = row0 + ai * HALF + m * 16; const float rs = rsv[ai][m]; bf16_t* rowp = O + (size_t)row * ldc + col0;
;                 const f32x4 g0 = acc[ai][0][m][0] * rs, g1 = acc[ai][0][m][1] * rs, u0 = acc[ai][1][m][0] * rs, u1 = acc[ai][1][m][1] * rs;
;                 u32x4 w; w.x = cvt_pk_bf16(sw(g0[0], u0[0]), sw(g0[1], u0[1])); w.y = cvt_pk_bf16(sw(g0[2], u0[2]), sw(g0[3], u0[3]));
;                 w.z = cvt_pk_bf16(sw(g1[0], u1[0]), sw(g1[1], u1[1])); w.w = cvt_pk_bf16(sw(g1[2], u1[2]), sw(g1[3], u1[3]));
;                 *(u32x4*)rowp = w; }
; template <class Epi, class Sched, bool ALIGN_EPI = false, bool SP2 = false>
; __device__ __forceinline__ void gemm_phase(PG8_LAS unsigned char* lds, const Gemm g, const Sched& S, const Epi& E) {
;     ...
;         if constexpr (!Epi::AFTER_DRAIN) { E(acc, cur, wr, wc, fr, fq); S.done(cur); }
;         if (!has_next) break;
; #pragma unroll
;         for (int a = 0; a < 2; ++a)
; #pragma unroll
;             for (int b = 0; b < 2; ++b)
; #pragma unroll
;                 for (int m = 0; m < 4; ++m)
; #pragma unroll
;                     for (int n = 0; n < 2; ++n) acc[a][b][m][n] = (f32x4){0.f, 0.f, 0.f, 0.f};
;         cur = nxt; cA = nA; cB = nB; ++ui;
;         if constexpr (ALIGN_EPI) { if (wr == 1) PG8_BAR; }
;     }
	v_add_f32_e32 v39, 1.0, v39
	v_rcp_f32_e32 v38, v38
	v_rcp_f32_e32 v39, v39
	v_pk_mul_f32 v[36:37], v[40:41], v[36:37]
	v_lshl_add_u64 v[48:49], v[48:49], 0, v[150:151]
	v_pk_mul_f32 v[34:35], v[34:35], v[36:37]
	v_pk_mul_f32 v[36:37], v[42:43], v[38:39]
	v_cvt_pk_bf16_f32 v34, v34, v35
	v_pk_mul_f32 v[36:37], v[50:51], v[36:37]
	v_pk_mul_f32 v[30:31], v[30:31], v[154:155] op_sel_hi:[1,0]
	v_cvt_pk_bf16_f32 v35, v36, v37
	global_store_dwordx4 v[48:49], v[32:35], off
	v_pk_mul_f32 v[20:21], v[20:21], v[154:155] op_sel_hi:[1,0]
	v_pk_mul_f32 v[24:25], v[24:25], v[154:155] op_sel_hi:[1,0]
	v_pk_mul_f32 v[34:35], v[18:19], v[154:155] op_sel_hi:[1,0]
	v_mul_f32_e32 v18, 0xbfb8aa3b, v28
	v_exp_f32_e32 v36, v18
	v_mul_f32_e32 v18, 0xbfb8aa3b, v29
	v_exp_f32_e32 v37, v18
	v_pk_mul_f32 v[18:19], v[16:17], v[154:155] op_sel_hi:[1,0]
	v_add_f32_e32 v16, 1.0, v36
	v_mul_f32_e32 v36, 0xbfb8aa3b, v30
	v_add_f32_e32 v17, 1.0, v37
	v_mul_f32_e32 v37, 0xbfb8aa3b, v31
	v_exp_f32_e32 v36, v36
	v_exp_f32_e32 v37, v37
	v_rcp_f32_e32 v16, v16
	v_rcp_f32_e32 v17, v17
	v_add_f32_e32 v36, 1.0, v36
	v_add_f32_e32 v37, 1.0, v37
	v_rcp_f32_e32 v36, v36
	v_rcp_f32_e32 v37, v37
	v_pk_mul_f32 v[16:17], v[28:29], v[16:17]
	v_pk_mul_f32 v[22:23], v[22:23], v[154:155] op_sel_hi:[1,0]
	v_pk_mul_f32 v[16:17], v[20:21], v[16:17]
	v_pk_mul_f32 v[20:21], v[30:31], v[36:37]
	v_cvt_pk_bf16_f32 v16, v16, v17
	v_mul_f32_e32 v17, 0xbfb8aa3b, v24
	v_pk_mul_f32 v[20:21], v[22:23], v[20:21]
	v_exp_f32_e32 v22, v17
	v_mul_f32_e32 v17, 0xbfb8aa3b, v25
	v_exp_f32_e32 v23, v17
	v_pk_mul_f32 v[26:27], v[26:27], v[154:155] op_sel_hi:[1,0]
	v_cvt_pk_bf16_f32 v17, v20, v21
	v_add_f32_e32 v20, 1.0, v22
	v_add_f32_e32 v21, 1.0, v23
	v_mul_f32_e32 v22, 0xbfb8aa3b, v26
	v_mul_f32_e32 v23, 0xbfb8aa3b, v27
	v_exp_f32_e32 v22, v22
	v_exp_f32_e32 v23, v23
	v_rcp_f32_e32 v20, v20
	v_rcp_f32_e32 v21, v21
	v_add_f32_e32 v22, 1.0, v22
	v_add_f32_e32 v23, 1.0, v23
	v_rcp_f32_e32 v22, v22
	v_rcp_f32_e32 v23, v23
	v_pk_mul_f32 v[20:21], v[24:25], v[20:21]
	v_mad_i64_i32 v[32:33], s[0:1], v153, s47, v[148:149]
	v_pk_mul_f32 v[18:19], v[18:19], v[20:21]
	v_pk_mul_f32 v[20:21], v[26:27], v[22:23]
	v_lshl_add_u64 v[32:33], v[32:33], 0, v[150:151]
	v_pk_mul_f32 v[20:21], v[34:35], v[20:21]
	v_cvt_pk_bf16_f32 v18, v18, v19
	v_cvt_pk_bf16_f32 v19, v20, v21
	v_pk_mul_f32 v[12:13], v[12:13], v[144:145] op_sel_hi:[1,0]
	global_store_dwordx4 v[32:33], v[16:19], off
	v_pk_mul_f32 v[14:15], v[14:15], v[144:145] op_sel_hi:[1,0]
	v_pk_mul_f32 v[4:5], v[4:5], v[144:145] op_sel_hi:[1,0]
	v_pk_mul_f32 v[18:19], v[2:3], v[144:145] op_sel_hi:[1,0]
	v_mul_f32_e32 v2, 0xbfb8aa3b, v12
	v_exp_f32_e32 v20, v2
	v_mul_f32_e32 v2, 0xbfb8aa3b, v13
	v_exp_f32_e32 v21, v2
	v_pk_mul_f32 v[2:3], v[0:1], v[144:145] op_sel_hi:[1,0]
	v_add_f32_e32 v0, 1.0, v20
	v_mul_f32_e32 v20, 0xbfb8aa3b, v14
	v_add_f32_e32 v1, 1.0, v21
	v_mul_f32_e32 v21, 0xbfb8aa3b, v15
	v_exp_f32_e32 v20, v20
	v_exp_f32_e32 v21, v21
	v_rcp_f32_e32 v0, v0
	v_rcp_f32_e32 v1, v1
	v_add_f32_e32 v20, 1.0, v20
	v_add_f32_e32 v21, 1.0, v21
	v_rcp_f32_e32 v20, v20
	v_rcp_f32_e32 v21, v21
	v_pk_mul_f32 v[0:1], v[12:13], v[0:1]
	v_pk_mul_f32 v[8:9], v[8:9], v[144:145] op_sel_hi:[1,0]
	v_pk_mul_f32 v[0:1], v[4:5], v[0:1]
	v_pk_mul_f32 v[6:7], v[6:7], v[144:145] op_sel_hi:[1,0]
	v_cvt_pk_bf16_f32 v0, v0, v1
	v_pk_mul_f32 v[4:5], v[14:15], v[20:21]
	v_mul_f32_e32 v1, 0xbfb8aa3b, v8
	v_pk_mul_f32 v[4:5], v[6:7], v[4:5]
	v_exp_f32_e32 v6, v1
	v_mul_f32_e32 v1, 0xbfb8aa3b, v9
	v_exp_f32_e32 v7, v1
	v_pk_mul_f32 v[10:11], v[10:11], v[144:145] op_sel_hi:[1,0]
	v_cvt_pk_bf16_f32 v1, v4, v5
	v_add_f32_e32 v4, 1.0, v6
	v_add_f32_e32 v5, 1.0, v7
	v_mul_f32_e32 v6, 0xbfb8aa3b, v10
	v_mul_f32_e32 v7, 0xbfb8aa3b, v11
	v_exp_f32_e32 v6, v6
	v_exp_f32_e32 v7, v7
	v_rcp_f32_e32 v4, v4
	v_rcp_f32_e32 v5, v5
	v_add_f32_e32 v6, 1.0, v6
	v_add_f32_e32 v7, 1.0, v7
	v_rcp_f32_e32 v6, v6
	v_rcp_f32_e32 v7, v7
	v_pk_mul_f32 v[4:5], v[8:9], v[4:5]
	v_mad_i64_i32 v[16:17], s[0:1], v147, s47, v[148:149]
	v_pk_mul_f32 v[2:3], v[2:3], v[4:5]
	v_pk_mul_f32 v[4:5], v[10:11], v[6:7]
	v_lshl_add_u64 v[16:17], v[16:17], 0, v[150:151]
	v_pk_mul_f32 v[4:5], v[18:19], v[4:5]
	v_cvt_pk_bf16_f32 v2, v2, v3
	v_cvt_pk_bf16_f32 v3, v4, v5
	s_andn2_b64 vcc, exec, s[6:7]
	s_mov_b64 s[0:1], -1
	global_store_dwordx4 v[16:17], v[0:3], off
	s_cbranch_vccnz .LBB0_745
	s_andn2_b64 vcc, exec, s[14:15]
	s_cbranch_vccnz .LBB0_744
	s_barrier
	s_branch .LBB0_744

; __device__ __forceinline__ float row_rstd(const float* __restrict__ rowss, int row) { const float ss = rowss[row]; return 1.0f / sqrtf(ss * (1.0f / 2048.0f) + 1e-6f); }
;     __host__ __device__ bool next(int i, Unit& u) const {
;         const long L = (long)i * G + c; if (L >= nwg) return false;
;         int wgid = (int)L; { const int q = nwg / NXCD, r = nwg % NXCD, xcd = wgid % NXCD, off = wgid / NXCD; wgid = (xcd < r ? xcd * (q + 1) : r * (q + 1) + (xcd - r) * q) + off; }
;         const int nig = WGM * nN, gid = wgid / nig, fm = gid * WGM, gsz = (nM - fm) < WGM ? (nM - fm) : WGM;
;         u.pm = fm + ((wgid % nig) % gsz); u.pn = (wgid % nig) / gsz; return true;
;     }
;     __device__ __forceinline__ void operator()(const f32x4 (&acc)[2][2][4][2], const Unit& u, int wr, int wc, int fr, int fq) const {
;     ...
;             for (int m = 0; m < 4; ++m) rsv[ai][m] = row_rstd(rowss, row0 + ai * HALF + m * 16);
.LBB0_912:
	v_lshl_add_u32 v0, s0, 8, v153
	v_ashrrev_i32_e32 v1, 31, v0
	v_lshl_add_u64 v[0:1], v[0:1], 2, s[18:19]
	global_load_dword v248, v[0:1], off
	global_load_dword v249, v[0:1], off offset:64
	global_load_dword v250, v[0:1], off offset:128
	global_load_dword v251, v[0:1], off offset:192
	global_load_dword v252, v[0:1], off offset:512
	global_load_dword v253, v[0:1], off offset:576
	global_load_dword v254, v[0:1], off offset:640
	global_load_dword v255, v[0:1], off offset:704
	s_add_i32 s41, s41, 1
	v_readlane_b32 s1, v247, 5
	s_mul_i32 s1, s41, s1
	s_mul_hi_u32 s6, s41, s33
	s_add_i32 s6, s6, s1
	s_mul_i32 s1, s41, s33
	s_add_u32 s10, s1, s82
	s_addc_u32 s11, s6, s3
	v_cmp_gt_i64_e32 vcc, s[10:11], v[142:143]
	v_cmp_lt_i64_e64 s[6:7], s[10:11], v[140:141]
	s_cbranch_vccnz .LBB0_914
	s_ashr_i32 s1, s10, 31
	s_lshr_b32 s1, s1, 29
	s_add_i32 s1, s10, s1
	s_ashr_i32 s11, s1, 3
	s_and_b32 s1, s1, -8
	s_sub_i32 s1, s10, s1
	s_cmp_lt_i32 s1, 0
	s_cselect_b32 s10, s36, 0xc0
	s_mul_i32 s1, s10, s1
	s_add_i32 s1, s1, s11
	s_mul_hi_i32 s10, s1, 0x2aaaaaab
	s_lshr_b32 s11, s10, 31
	s_ashr_i32 s10, s10, 5
	s_add_i32 s10, s10, s11
	s_lshl_b32 s11, s10, 3
	s_sub_i32 s24, 64, s11
	s_min_i32 s25, s24, 8
	s_abs_i32 s24, s25
	v_cvt_f32_u32_e32 v0, s24
	s_sub_i32 s27, 0, s24
	s_mulk_i32 s10, 0xc0
	s_sub_i32 s1, s1, s10
	v_rcp_iflag_f32_e32 v0, v0
	s_abs_i32 s10, s1
	s_xor_b32 s26, s1, s25
	s_ashr_i32 s26, s26, 31
	v_mul_f32_e32 v0, 0x4f7ffffe, v0
	v_cvt_u32_f32_e32 v0, v0
	s_nop 0
	v_readfirstlane_b32 s28, v0
	s_mul_i32 s27, s27, s28
	s_mul_hi_u32 s27, s28, s27
	s_add_i32 s28, s28, s27
	s_mul_hi_u32 s27, s10, s28
	s_mul_i32 s28, s27, s24
	s_sub_i32 s10, s10, s28
	s_add_i32 s29, s27, 1
	s_sub_i32 s28, s10, s24
	s_cmp_ge_u32 s10, s24
	s_cselect_b32 s27, s29, s27
	s_cselect_b32 s10, s28, s10
	s_add_i32 s28, s27, 1
	s_cmp_ge_u32 s10, s24
	s_cselect_b32 s10, s28, s27
	s_xor_b32 s10, s10, s26
	s_sub_i32 s24, s10, s26
	s_mul_i32 s10, s24, s25
	s_sub_i32 s1, s1, s10
	s_add_i32 s26, s1, s11

; #define PG8_STAGE(bufoff, gbase, voff) do { _Pragma("unroll") for (int _i = 0; _i < 2; ++_i) \
;         __builtin_amdgcn_global_load_lds((const unsigned*)((const char*)(gbase) + (voff)[_i]), (PG8_LAS unsigned*)(lds + (bufoff) + ldsw + _i * 8192), 16, 0, 0); } while (0)
; #define PG8_LDA(dst, b, h) do { _Pragma("unroll") for (int m = 0; m < 4; ++m) _Pragma("unroll") for (int k = 0; k < 2; ++k) dst[m][k] = *(const PG8_LAS bf16x8*)(lds + PG8_SA(b, h) + aoff + m * 2048 + k * 1024); } while (0)
; #define PG8_LDB(dst, b, h) do { _Pragma("unroll") for (int n = 0; n < 2; ++n) _Pragma("unroll") for (int k = 0; k < 2; ++k) dst[n][k] = *(const PG8_LAS bf16x8*)(lds + PG8_SB(b, h) + boff + n * 2048 + k * 1024); } while (0)
; #define PG8_MMA(ai, bj, At, Bt) do { __builtin_amdgcn_s_setprio(1); _Pragma("unroll") for (int m = 0; m < 4; ++m) _Pragma("unroll") for (int n = 0; n < 2; ++n) _Pragma("unroll") for (int k = 0; k < 2; ++k) \
;         acc[ai][bj][m][n] = __builtin_amdgcn_mfma_f32_16x16x32_bf16(Bt[n][k], At[m][k], acc[ai][bj][m][n], 0, 0, 0); __builtin_amdgcn_s_setprio(0); } while (0)
; #define PG8_WAIT_V(n) asm volatile("s_waitcnt vmcnt(" #n ")" ::: "memory")
; #define PG8_WAIT_L(n) asm volatile("s_waitcnt lgkmcnt(" #n ")" ::: "memory")
; #define PG8_BAR __builtin_amdgcn_s_barrier()
; #define PG8_SCHED __builtin_amdgcn_sched_barrier(0)
; template <class Epi, class Sched, bool ALIGN_EPI = false, bool SP2 = false>
; __device__ __forceinline__ void gemm_phase(PG8_LAS unsigned char* lds, const Gemm g, const Sched& S, const Epi& E) {
;     ...
;             const bool last = (t == nt - 2);
;             const char* a1 = cA + (size_t)(t + 1) * kstep;
;             const char* a2 = last ? nA : cA + (size_t)(t + 2) * kstep; const char* b2 = last ? nB : cB + (size_t)(t + 2) * kstep;
;             const char* a3 = a2 + kstep; const char* b3 = b2 + kstep;
;             if (last && has_next) S.a_ready(nxt);
;             if constexpr (SP2) {
;             PG8_LDB(B0, 0, 0); PG8_LDB(B1, 0, 1); PG8_SCHED; PG8_LDA(At, 0, 0); PG8_STAGE(PG8_SA(1, 1), a1 + hstep, voffA);
;             PG8_WAIT_V(8); PG8_WAIT_L(0); PG8_BAR; PG8_MMA(0, 0, At, B0); PG8_MMA(0, 1, At, B1); PG8_BAR; PG8_SCHED;
.LBB0_915:
	ds_read_b128 v[144:147], v161
	ds_read_b128 v[148:151], v161 offset:1024
	ds_read_b128 v[166:169], v161 offset:2048
	ds_read_b128 v[170:173], v161 offset:3072
	ds_read_b128 v[174:177], v162
	ds_read_b128 v[178:181], v162 offset:1024
	ds_read_b128 v[182:185], v162 offset:2048
	ds_read_b128 v[186:189], v162 offset:3072
	s_add_u32 s10, s8, 0xfff80080
	s_addc_u32 s11, s9, -1
	s_cmp_eq_u32 s52, 28
	s_cselect_b32 s13, s1, s11
	s_cselect_b32 s12, s27, s10
	s_cselect_b32 s11, s25, s51
	s_cselect_b32 s10, s49, s50
	v_lshl_add_u64 v[158:159], s[8:9], 0, v[136:137]
	s_add_i32 m0, s37, 0xc000
	ds_read_b128 v[190:193], v163
	ds_read_b128 v[194:197], v163 offset:1024
	ds_read_b128 v[198:201], v163 offset:2048
	ds_read_b128 v[206:209], v163 offset:3072
	ds_read_b128 v[210:213], v163 offset:4096
	ds_read_b128 v[214:217], v163 offset:5120
	ds_read_b128 v[218:221], v163 offset:6144
	ds_read_b128 v[222:225], v163 offset:7168
	global_load_lds_dwordx4 v[158:159], off
	v_lshl_add_u64 v[158:159], s[8:9], 0, v[138:139]
	s_add_i32 m0, s37, 0xe000
	s_nop 0
	global_load_lds_dwordx4 v[158:159], off
	s_cmp_lg_u32 s52, -2
	s_cbranch_scc1 .Lgw_norm_915_0
	s_cmp_eq_u32 s41, 1
	s_cbranch_scc1 .Lgw_norm_915_0
	s_waitcnt vmcnt(32)
	s_branch .Lgw_join_915_0

; #define PG8_STAGE(bufoff, gbase, voff) do { _Pragma("unroll") for (int _i = 0; _i < 2; ++_i) \
;         __builtin_amdgcn_global_load_lds((const unsigned*)((const char*)(gbase) + (voff)[_i]), (PG8_LAS unsigned*)(lds + (bufoff) + ldsw + _i * 8192), 16, 0, 0); } while (0)
; #define PG8_LDA(dst, b, h) do { _Pragma("unroll") for (int m = 0; m < 4; ++m) _Pragma("unroll") for (int k = 0; k < 2; ++k) dst[m][k] = *(const PG8_LAS bf16x8*)(lds + PG8_SA(b, h) + aoff + m * 2048 + k * 1024); } while (0)
; #define PG8_MMA(ai, bj, At, Bt) do { __builtin_amdgcn_s_setprio(1); _Pragma("unroll") for (int m = 0; m < 4; ++m) _Pragma("unroll") for (int n = 0; n < 2; ++n) _Pragma("unroll") for (int k = 0; k < 2; ++k) \
;         acc[ai][bj][m][n] = __builtin_amdgcn_mfma_f32_16x16x32_bf16(Bt[n][k], At[m][k], acc[ai][bj][m][n], 0, 0, 0); __builtin_amdgcn_s_setprio(0); } while (0)
; #define PG8_WAIT_V(n) asm volatile("s_waitcnt vmcnt(" #n ")" ::: "memory")
; #define PG8_WAIT_L(n) asm volatile("s_waitcnt lgkmcnt(" #n ")" ::: "memory")
; #define PG8_BAR __builtin_amdgcn_s_barrier()
; #define PG8_SCHED __builtin_amdgcn_sched_barrier(0)
; template <class Epi, class Sched, bool ALIGN_EPI = false, bool SP2 = false>
; __device__ __forceinline__ void gemm_phase(PG8_LAS unsigned char* lds, const Gemm g, const Sched& S, const Epi& E) {
;     ...
;             PG8_WAIT_V(8); PG8_WAIT_L(0); PG8_BAR; PG8_MMA(0, 0, At, B0); PG8_MMA(0, 1, At, B1); PG8_BAR; PG8_SCHED;
;             PG8_LDA(At, 0, 1); PG8_STAGE(PG8_SB(0, 0), b2, voffB); PG8_STAGE(PG8_SB(0, 1), b2 + hstep, voffB); PG8_STAGE(PG8_SA(0, 0), a2, voffA);
;             PG8_WAIT_V(8); PG8_WAIT_L(0); PG8_BAR; PG8_MMA(1, 0, At, B0); PG8_MMA(1, 1, At, B1); PG8_BAR; PG8_SCHED;
.Lgw_join_915_0:
	s_waitcnt lgkmcnt(0)
	s_barrier
	s_setprio 1
	s_waitcnt lgkmcnt(0)
	v_mfma_f32_16x16x32_bf16 v[124:127], v[144:147], v[190:193], v[124:127]
	v_mfma_f32_16x16x32_bf16 v[120:123], v[166:169], v[190:193], v[120:123]
	v_mfma_f32_16x16x32_bf16 v[116:119], v[144:147], v[198:201], v[116:119]
	v_mfma_f32_16x16x32_bf16 v[108:111], v[166:169], v[198:201], v[108:111]
	v_mfma_f32_16x16x32_bf16 v[100:103], v[144:147], v[210:213], v[100:103]
	v_mfma_f32_16x16x32_bf16 v[92:95], v[166:169], v[210:213], v[92:95]
	v_mfma_f32_16x16x32_bf16 v[84:87], v[144:147], v[218:221], v[84:87]
	v_mfma_f32_16x16x32_bf16 v[76:79], v[166:169], v[218:221], v[76:79]
	v_mfma_f32_16x16x32_bf16 v[124:127], v[148:151], v[194:197], v[124:127]
	v_mfma_f32_16x16x32_bf16 v[120:123], v[170:173], v[194:197], v[120:123]
	v_mfma_f32_16x16x32_bf16 v[116:119], v[148:151], v[206:209], v[116:119]
	v_mfma_f32_16x16x32_bf16 v[108:111], v[170:173], v[206:209], v[108:111]
	v_mfma_f32_16x16x32_bf16 v[100:103], v[148:151], v[214:217], v[100:103]
	v_mfma_f32_16x16x32_bf16 v[92:95], v[170:173], v[214:217], v[92:95]
	v_mfma_f32_16x16x32_bf16 v[84:87], v[148:151], v[222:225], v[84:87]
	v_mfma_f32_16x16x32_bf16 v[76:79], v[170:173], v[222:225], v[76:79]
	s_setprio 0
	s_setprio 1
	v_mfma_f32_16x16x32_bf16 v[112:115], v[174:177], v[190:193], v[112:115]
	v_mfma_f32_16x16x32_bf16 v[104:107], v[182:185], v[190:193], v[104:107]
	v_mfma_f32_16x16x32_bf16 v[96:99], v[174:177], v[198:201], v[96:99]
	v_mfma_f32_16x16x32_bf16 v[88:91], v[182:185], v[198:201], v[88:91]
	v_mfma_f32_16x16x32_bf16 v[80:83], v[174:177], v[210:213], v[80:83]
	v_mfma_f32_16x16x32_bf16 v[72:75], v[182:185], v[210:213], v[72:75]
	v_mfma_f32_16x16x32_bf16 v[68:71], v[174:177], v[218:221], v[68:71]
	v_mfma_f32_16x16x32_bf16 v[64:67], v[182:185], v[218:221], v[64:67]
	v_mfma_f32_16x16x32_bf16 v[112:115], v[178:181], v[194:197], v[112:115]
	v_mfma_f32_16x16x32_bf16 v[104:107], v[186:189], v[194:197], v[104:107]
	v_mfma_f32_16x16x32_bf16 v[96:99], v[178:181], v[206:209], v[96:99]
	v_mfma_f32_16x16x32_bf16 v[88:91], v[186:189], v[206:209], v[88:91]
	v_mfma_f32_16x16x32_bf16 v[80:83], v[178:181], v[214:217], v[80:83]
	v_mfma_f32_16x16x32_bf16 v[72:75], v[186:189], v[214:217], v[72:75]
	v_mfma_f32_16x16x32_bf16 v[68:71], v[178:181], v[222:225], v[68:71]
	v_mfma_f32_16x16x32_bf16 v[64:67], v[186:189], v[222:225], v[64:67]
	s_setprio 0
	s_barrier
	s_add_i32 s53, s44, s35
	v_lshl_add_u64 v[158:159], s[10:11], 0, v[132:133]
	s_mov_b32 m0, s53
	ds_read_b128 v[190:193], v163 offset:16384
	ds_read_b128 v[194:197], v163 offset:17408
	ds_read_b128 v[198:201], v163 offset:18432
	ds_read_b128 v[206:209], v163 offset:19456
	ds_read_b128 v[210:213], v163 offset:20480
	ds_read_b128 v[214:217], v163 offset:21504
	ds_read_b128 v[218:221], v163 offset:22528
	ds_read_b128 v[222:225], v163 offset:23552
	global_load_lds_dwordx4 v[158:159], off
	s_add_i32 m0, s53, 0x2000
	s_add_u32 s54, s10, 0x80000
	v_lshl_add_u64 v[202:203], s[10:11], 0, v[128:129]
	s_addc_u32 s55, s11, 0
	s_add_i32 s53, s45, s35
	global_load_lds_dwordx4 v[202:203], off
	v_lshl_add_u64 v[226:227], s[54:55], 0, v[132:133]
	s_mov_b32 m0, s53
	v_lshl_add_u64 v[228:229], s[12:13], 0, v[130:131]
	global_load_lds_dwordx4 v[226:227], off
	v_lshl_add_u64 v[226:227], s[54:55], 0, v[128:129]
	s_add_i32 m0, s53, 0x2000
	s_nop 0
	global_load_lds_dwordx4 v[226:227], off
	v_lshl_add_u64 v[226:227], s[12:13], 0, v[134:135]
	s_mov_b32 m0, s37
	s_nop 0
	global_load_lds_dwordx4 v[226:227], off
	s_mov_b32 m0, s38
	s_nop 0
	global_load_lds_dwordx4 v[228:229], off
	s_cmp_lg_u32 s52, -2
	s_cbranch_scc1 .Lgw_norm_915_1
	s_cmp_eq_u32 s41, 1
	s_cbranch_scc1 .Lgw_norm_915_1
	s_waitcnt vmcnt(32)
	s_branch .Lgw_join_915_1

; __device__ __forceinline__ float row_rstd(const float* __restrict__ rowss, int row) { const float ss = rowss[row]; return 1.0f / sqrtf(ss * (1.0f / 2048.0f) + 1e-6f); }
;     __device__ __forceinline__ void operator()(const f32x4 (&acc)[2][2][4][2], const Unit& u, int wr, int wc, int fr, int fq) const {
;     ...
;         float rsv[2][4];
; #pragma unroll
;         for (int ai = 0; ai < 2; ++ai)
; #pragma unroll
;             for (int m = 0; m < 4; ++m) rsv[ai][m] = row_rstd(rowss, row0 + ai * HALF + m * 16);
.LBB0_918:
	v_lshl_add_u32 v150, s0, 8, v153
	v_ashrrev_i32_e32 v151, 31, v150
	v_lshl_add_u64 v[158:159], v[150:151], 2, s[18:19]
	v_mov_b32_e32 v151, v248
	v_or_b32_e32 v144, 16, v150
	v_ashrrev_i32_e32 v145, 31, v144
	v_or_b32_e32 v146, 32, v150
	v_or_b32_e32 v148, 48, v150
	v_lshl_add_u64 v[166:167], v[144:145], 2, s[18:19]
	v_ashrrev_i32_e32 v147, 31, v146
	v_ashrrev_i32_e32 v149, 31, v148
	v_lshl_add_u64 v[168:169], v[146:147], 2, s[18:19]
	v_lshl_add_u64 v[170:171], v[148:149], 2, s[18:19]
	v_mov_b32_e32 v145, v249
	v_mov_b32_e32 v147, v250
	v_mov_b32_e32 v149, v251
	v_mov_b32_e32 v152, v252
	v_mov_b32_e32 v154, v253
	v_mov_b32_e32 v156, v254
	s_nop 0
	v_mov_b32_e32 v158, v255
	s_nop 0
	v_fmamk_f32 v151, v151, 0x3a000000, v164
	v_mul_f32_e32 v159, 0x4f800000, v151
	v_cmp_gt_f32_e32 vcc, s46, v151
	v_fmamk_f32 v145, v145, 0x3a000000, v164
	s_nop 0
	v_cndmask_b32_e32 v151, v151, v159, vcc
	v_fmamk_f32 v147, v147, 0x3a000000, v164
	v_mul_f32_e32 v159, 0x4f800000, v145
	v_sqrt_f32_e32 v167, v151
	v_cmp_gt_f32_e64 s[0:1], s46, v145
	v_mul_f32_e32 v160, 0x4f800000, v147
	v_cmp_gt_f32_e64 s[8:9], s46, v147
	v_cndmask_b32_e64 v145, v145, v159, s[0:1]
	v_fmamk_f32 v149, v149, 0x3a000000, v164
	v_cndmask_b32_e64 v147, v147, v160, s[8:9]
	v_sqrt_f32_e32 v159, v145
	v_mul_f32_e32 v166, 0x4f800000, v149
	v_cmp_gt_f32_e64 s[10:11], s46, v149
	v_sqrt_f32_e32 v160, v147
	v_add_u32_e32 v168, 1, v167
	v_cndmask_b32_e64 v149, v149, v166, s[10:11]
	v_add_u32_e32 v166, -1, v167
	v_fma_f32 v169, -v166, v167, v151
	v_fma_f32 v170, -v168, v167, v151
	v_add_u32_e32 v171, -1, v159
	v_cmp_ge_f32_e64 s[12:13], 0, v169
	v_add_u32_e32 v173, -1, v160
	v_add_u32_e32 v172, 1, v159
	v_cndmask_b32_e64 v166, v167, v166, s[12:13]
	v_fma_f32 v167, -v171, v159, v145
	v_cmp_lt_f32_e64 s[12:13], 0, v170
	v_fma_f32 v175, -v173, v160, v147
	v_add_u32_e32 v174, 1, v160
	v_cndmask_b32_e64 v166, v166, v168, s[12:13]
	v_cmp_ge_f32_e64 s[12:13], 0, v167
	v_fma_f32 v169, -v172, v159, v145
	v_fma_f32 v176, -v174, v160, v147
	v_cndmask_b32_e64 v159, v159, v171, s[12:13]
	v_cmp_ge_f32_e64 s[12:13], 0, v175
	v_mul_f32_e32 v167, 0x37800000, v166
	v_cndmask_b32_e32 v166, v166, v167, vcc
	v_cndmask_b32_e64 v160, v160, v173, s[12:13]
	v_cmp_lt_f32_e64 s[12:13], 0, v169
	v_cmp_class_f32_e32 vcc, v151, v165
	v_fmamk_f32 v152, v152, 0x3a000000, v164
	v_cndmask_b32_e64 v159, v159, v172, s[12:13]
	v_cmp_lt_f32_e64 s[12:13], 0, v176
	v_mul_f32_e32 v167, 0x37800000, v159
	v_cndmask_b32_e32 v151, v166, v151, vcc
	v_cndmask_b32_e64 v160, v160, v174, s[12:13]
	v_cndmask_b32_e64 v159, v159, v167, s[0:1]
	v_div_scale_f32 v166, s[0:1], v151, v151, 1.0
	v_mul_f32_e32 v168, 0x37800000, v160
	v_cmp_class_f32_e64 s[0:1], v145, v165
	v_cndmask_b32_e64 v160, v160, v168, s[8:9]
	v_div_scale_f32 v167, vcc, 1.0, v151, 1.0
	v_cndmask_b32_e64 v145, v159, v145, s[0:1]
	v_cmp_class_f32_e64 s[0:1], v147, v165
	v_rcp_f32_e32 v159, v166
	v_fmamk_f32 v154, v154, 0x3a000000, v164
	v_cndmask_b32_e64 v147, v160, v147, s[0:1]
	v_div_scale_f32 v160, s[0:1], v145, v145, 1.0
	v_div_scale_f32 v169, s[8:9], v147, v147, 1.0
	v_rcp_f32_e32 v171, v160
	v_rcp_f32_e32 v172, v169
	v_fma_f32 v173, -v166, v159, 1.0
	v_fmac_f32_e32 v159, v173, v159
	v_fma_f32 v173, -v160, v171, 1.0
	v_div_scale_f32 v168, s[0:1], 1.0, v145, 1.0
	v_fma_f32 v174, -v169, v172, 1.0
	v_mul_f32_e32 v175, v167, v159
	v_fmac_f32_e32 v171, v173, v171
	v_fmac_f32_e32 v172, v174, v172
	v_fma_f32 v173, -v166, v175, v167
	v_mul_f32_e32 v174, v168, v171
	v_fmac_f32_e32 v175, v173, v159
	v_fma_f32 v173, -v160, v174, v168
	v_fma_f32 v166, -v166, v175, v167
	v_fmac_f32_e32 v174, v173, v171
	v_div_fmas_f32 v159, v166, v159, v175
	v_fma_f32 v160, -v160, v174, v168
	s_mov_b64 vcc, s[0:1]
	v_div_fixup_f32 v166, v159, v151, 1.0
	v_div_fmas_f32 v151, v160, v171, v174
	v_div_fixup_f32 v168, v151, v145, 1.0
	v_sqrt_f32_e32 v145, v149
	v_div_scale_f32 v170, s[8:9], 1.0, v147, 1.0
	v_mul_f32_e32 v176, v170, v172
	v_add_u32_e32 v159, -1, v145
	v_fma_f32 v160, -v159, v145, v149
	v_cmp_ge_f32_e32 vcc, 0, v160
	v_add_u32_e32 v160, 1, v145
	v_fma_f32 v151, -v169, v176, v170
	v_cndmask_b32_e32 v159, v145, v159, vcc
	v_fma_f32 v145, -v160, v145, v149
	v_cmp_lt_f32_e32 vcc, 0, v145
	v_fmac_f32_e32 v176, v151, v172
	v_fma_f32 v151, -v169, v176, v170
	v_cndmask_b32_e32 v145, v159, v160, vcc
	v_mul_f32_e32 v159, 0x37800000, v145
	v_cndmask_b32_e64 v145, v145, v159, s[10:11]
	v_cmp_class_f32_e32 vcc, v149, v165
	v_mul_f32_e32 v160, 0x4f800000, v152
	v_fmamk_f32 v156, v156, 0x3a000000, v164
	v_cndmask_b32_e32 v145, v145, v149, vcc
	v_div_scale_f32 v149, s[0:1], v145, v145, 1.0
	v_rcp_f32_e32 v159, v149
	s_mov_b64 vcc, s[8:9]
	v_div_fmas_f32 v151, v151, v172, v176
	v_cmp_gt_f32_e64 s[0:1], s46, v152
	v_div_fixup_f32 v170, v151, v147, 1.0
	v_fma_f32 v147, -v149, v159, 1.0
	v_cndmask_b32_e64 v152, v152, v160, s[0:1]
	v_fmac_f32_e32 v159, v147, v159
	v_div_scale_f32 v147, vcc, 1.0, v145, 1.0
	v_sqrt_f32_e32 v160, v152
	v_mul_f32_e32 v151, v147, v159
	v_fma_f32 v167, -v149, v151, v147
	v_fmac_f32_e32 v151, v167, v159
	v_fma_f32 v147, -v149, v151, v147
	v_add_u32_e32 v149, -1, v160
	v_fma_f32 v167, -v149, v160, v152
	v_cmp_ge_f32_e64 s[8:9], 0, v167
	v_add_u32_e32 v167, 1, v160
	v_div_fmas_f32 v147, v147, v159, v151
	v_cndmask_b32_e64 v149, v160, v149, s[8:9]
	v_fma_f32 v160, -v167, v160, v152
	v_cmp_lt_f32_e64 s[8:9], 0, v160
	v_mul_f32_e32 v159, 0x4f800000, v154
	v_div_fixup_f32 v172, v147, v145, 1.0
	v_cndmask_b32_e64 v149, v149, v167, s[8:9]
	v_mul_f32_e32 v160, 0x37800000, v149
	v_cndmask_b32_e64 v149, v149, v160, s[0:1]
	v_cmp_class_f32_e64 s[0:1], v152, v165
	v_fmamk_f32 v158, v158, 0x3a000000, v164
; __device__ __forceinline__ unsigned cvt_pk_bf16(float lo, float hi) { typedef float f2_t __attribute__((ext_vector_type(2))); typedef __bf16 b2_t __attribute__((ext_vector_type(2))); f2_t v = {lo, hi}; b2_t b = __builtin_convertvector(v, b2_t); return __builtin_bit_cast(unsigned, b); }
; __device__ __forceinline__ float row_rstd(const float* __restrict__ rowss, int row) { const float ss = rowss[row]; return 1.0f / sqrtf(ss * (1.0f / 2048.0f) + 1e-6f); }
;     __device__ __forceinline__ void operator()(const f32x4 (&acc)[2][2][4][2], const Unit& u, int wr, int wc, int fr, int fq) const {
;     ...
;             for (int m = 0; m < 4; ++m) rsv[ai][m] = row_rstd(rowss, row0 + ai * HALF + m * 16);
; #pragma unroll
;         for (int ai = 0; ai < 2; ++ai)
; #pragma unroll
;             for (int m = 0; m < 4; ++m) { const int row = row0 + ai * HALF + m * 16; const float rs = rsv[ai][m]; bf16_t* rowp = O + (size_t)row * ldc + col0;
; #pragma unroll
;                 for (int bj = 0; bj < 2; ++bj) { const f32x4 v0 = acc[ai][bj][m][0] * rs, v1 = acc[ai][bj][m][1] * rs;
;                     u32x4 w; w.x = cvt_pk_bf16(v0[0], v0[1]); w.y = cvt_pk_bf16(v0[2], v0[3]); w.z = cvt_pk_bf16(v1[0], v1[1]); w.w = cvt_pk_bf16(v1[2], v1[3]);
;                     *(u32x4*)(rowp + bj * HALF) = w; } }
	v_lshl_or_b32 v174, s48, 8, v157
	v_cndmask_b32_e64 v149, v149, v152, s[0:1]
	v_div_scale_f32 v152, s[0:1], v149, v149, 1.0
	v_rcp_f32_e32 v160, v152
	v_cmp_gt_f32_e64 s[0:1], s46, v154
	v_ashrrev_i32_e32 v175, 31, v174
	v_add_u32_e32 v145, 0x80, v150
	v_fma_f32 v147, -v152, v160, 1.0
	v_cndmask_b32_e64 v154, v154, v159, s[0:1]
	v_fmac_f32_e32 v160, v147, v160
	v_div_scale_f32 v147, vcc, 1.0, v149, 1.0
	v_sqrt_f32_e32 v159, v154
	v_mul_f32_e32 v151, v147, v160
	v_fma_f32 v167, -v152, v151, v147
	v_fmac_f32_e32 v151, v167, v160
	v_fma_f32 v147, -v152, v151, v147
	v_add_u32_e32 v152, -1, v159
	v_fma_f32 v167, -v152, v159, v154
	v_cmp_ge_f32_e64 s[8:9], 0, v167
	v_add_u32_e32 v167, 1, v159
	v_div_fmas_f32 v147, v147, v160, v151
	v_cndmask_b32_e64 v152, v159, v152, s[8:9]
	v_fma_f32 v159, -v167, v159, v154
	v_cmp_lt_f32_e64 s[8:9], 0, v159
	v_div_fixup_f32 v160, v147, v149, 1.0
	v_add_u32_e32 v147, 0x90, v150
	v_cndmask_b32_e64 v152, v152, v167, s[8:9]
	v_mul_f32_e32 v159, 0x37800000, v152
	v_cndmask_b32_e64 v152, v152, v159, s[0:1]
	v_cmp_class_f32_e64 s[0:1], v154, v165
	v_mul_f32_e32 v167, 0x4f800000, v156
	v_pk_mul_f32 v[78:79], v[78:79], v[172:173] op_sel_hi:[1,0]
	v_cndmask_b32_e64 v152, v152, v154, s[0:1]
	v_div_scale_f32 v154, s[0:1], v152, v152, 1.0
	v_rcp_f32_e32 v159, v154
	v_cmp_gt_f32_e64 s[0:1], s46, v156
	v_pk_mul_f32 v[76:77], v[76:77], v[172:173] op_sel_hi:[1,0]
	v_pk_mul_f32 v[70:71], v[70:71], v[172:173] op_sel_hi:[1,0]
	v_fma_f32 v149, -v154, v159, 1.0
	v_cndmask_b32_e64 v156, v156, v167, s[0:1]
	v_fmac_f32_e32 v159, v149, v159
	v_div_scale_f32 v149, vcc, 1.0, v152, 1.0
	v_sqrt_f32_e32 v167, v156
	v_mul_f32_e32 v151, v149, v159
	v_fma_f32 v169, -v154, v151, v149
	v_fmac_f32_e32 v151, v169, v159
	v_fma_f32 v149, -v154, v151, v149
	v_add_u32_e32 v154, -1, v167
	v_fma_f32 v169, -v154, v167, v156
	v_cmp_ge_f32_e64 s[8:9], 0, v169
	v_add_u32_e32 v169, 1, v167
	v_div_fmas_f32 v149, v149, v159, v151
	v_cndmask_b32_e64 v154, v167, v154, s[8:9]
	v_fma_f32 v167, -v169, v167, v156
	v_cmp_lt_f32_e64 s[8:9], 0, v167
	v_mul_f32_e32 v159, 0x4f800000, v158
	v_pk_mul_f32 v[68:69], v[68:69], v[172:173] op_sel_hi:[1,0]
	v_cndmask_b32_e64 v154, v154, v169, s[8:9]
	v_mul_f32_e32 v167, 0x37800000, v154
	v_cndmask_b32_e64 v154, v154, v167, s[0:1]
	v_cmp_class_f32_e64 s[0:1], v156, v165
	v_pk_mul_f32 v[62:63], v[62:63], v[160:161] op_sel_hi:[1,0]
	v_pk_mul_f32 v[60:61], v[60:61], v[160:161] op_sel_hi:[1,0]
	v_cndmask_b32_e64 v154, v154, v156, s[0:1]
	v_div_scale_f32 v167, s[0:1], v154, v154, 1.0
	v_rcp_f32_e32 v169, v167
	v_cmp_gt_f32_e64 s[0:1], s46, v158
	v_div_fixup_f32 v156, v149, v152, 1.0
	v_add_u32_e32 v149, 0xa0, v150
	v_fma_f32 v151, -v167, v169, 1.0
	v_cndmask_b32_e64 v158, v158, v159, s[0:1]
	v_fmac_f32_e32 v169, v151, v169
	v_div_scale_f32 v151, vcc, 1.0, v154, 1.0
	v_sqrt_f32_e32 v159, v158
	v_mul_f32_e32 v152, v151, v169
	v_fma_f32 v171, -v167, v152, v151
	v_fmac_f32_e32 v152, v171, v169
	v_fma_f32 v151, -v167, v152, v151
	v_add_u32_e32 v167, -1, v159
	v_fma_f32 v171, -v167, v159, v158
	v_cmp_ge_f32_e64 s[8:9], 0, v171
	v_add_u32_e32 v171, 1, v159
	v_div_fmas_f32 v151, v151, v169, v152
	v_cndmask_b32_e64 v167, v159, v167, s[8:9]
	v_fma_f32 v159, -v171, v159, v158
	v_cmp_lt_f32_e64 s[8:9], 0, v159
	v_div_fixup_f32 v154, v151, v154, 1.0
	v_add_u32_e32 v169, 0xb0, v150
	v_cndmask_b32_e64 v159, v167, v171, s[8:9]
	v_mul_f32_e32 v167, 0x37800000, v159
	v_cndmask_b32_e64 v159, v159, v167, s[0:1]
	v_cmp_class_f32_e64 s[0:1], v158, v165
	v_pk_mul_f32 v[110:111], v[110:111], v[168:169] op_sel_hi:[1,0]
	v_pk_mul_f32 v[108:109], v[108:109], v[168:169] op_sel_hi:[1,0]
	v_cndmask_b32_e64 v158, v159, v158, s[0:1]
	v_div_scale_f32 v159, s[0:1], v158, v158, 1.0
	v_rcp_f32_e32 v167, v159
	v_pk_mul_f32 v[98:99], v[98:99], v[168:169] op_sel_hi:[1,0]
	v_pk_mul_f32 v[96:97], v[96:97], v[168:169] op_sel_hi:[1,0]
	v_pk_mul_f32 v[50:51], v[50:51], v[160:161] op_sel_hi:[1,0]
	v_fma_f32 v151, -v159, v167, 1.0
	v_fmac_f32_e32 v167, v151, v167
	v_div_scale_f32 v151, vcc, 1.0, v158, 1.0
	v_mul_f32_e32 v152, v151, v167
	v_fma_f32 v171, -v159, v152, v151
	v_fmac_f32_e32 v152, v171, v167
	v_fma_f32 v151, -v159, v152, v151
	v_div_fmas_f32 v151, v151, v167, v152
	v_div_fixup_f32 v152, v151, v158, 1.0
	v_mov_b64_e32 v[158:159], s[16:17]
	v_mad_i64_i32 v[176:177], s[0:1], v150, s47, v[158:159]
	v_lshlrev_b64 v[150:151], 1, v[174:175]
	v_lshl_add_u64 v[174:175], v[176:177], 0, v[150:151]
	v_pk_mul_f32 v[126:127], v[126:127], v[166:167] op_sel_hi:[1,0]
	v_pk_mul_f32 v[124:125], v[124:125], v[166:167] op_sel_hi:[1,0]
	v_pk_mul_f32 v[176:177], v[122:123], v[166:167] op_sel_hi:[1,0]
	v_pk_mul_f32 v[122:123], v[120:121], v[166:167] op_sel_hi:[1,0]
	v_cvt_pk_bf16_f32 v120, v124, v125
	v_cvt_pk_bf16_f32 v121, v126, v127
	v_cvt_pk_bf16_f32 v122, v122, v123
	v_cvt_pk_bf16_f32 v123, v176, v177
	global_store_dwordx4 v[174:175], v[120:123], off
	v_pk_mul_f32 v[114:115], v[114:115], v[166:167] op_sel_hi:[1,0]
	v_pk_mul_f32 v[112:113], v[112:113], v[166:167] op_sel_hi:[1,0]
	v_pk_mul_f32 v[120:121], v[106:107], v[166:167] op_sel_hi:[1,0]
	v_pk_mul_f32 v[106:107], v[104:105], v[166:167] op_sel_hi:[1,0]
	v_cvt_pk_bf16_f32 v104, v112, v113
	v_cvt_pk_bf16_f32 v105, v114, v115
	v_cvt_pk_bf16_f32 v106, v106, v107
	v_cvt_pk_bf16_f32 v107, v120, v121
	global_store_dwordx4 v[174:175], v[104:107], off offset:256
	v_pk_mul_f32 v[94:95], v[94:95], v[170:171] op_sel_hi:[1,0]
	v_pk_mul_f32 v[92:93], v[92:93], v[170:171] op_sel_hi:[1,0]
	v_mad_i64_i32 v[104:105], s[0:1], v144, s47, v[158:159]
	v_lshl_add_u64 v[112:113], v[104:105], 0, v[150:151]
	v_pk_mul_f32 v[106:107], v[118:119], v[168:169] op_sel_hi:[1,0]
; __device__ __forceinline__ unsigned cvt_pk_bf16(float lo, float hi) { typedef float f2_t __attribute__((ext_vector_type(2))); typedef __bf16 b2_t __attribute__((ext_vector_type(2))); f2_t v = {lo, hi}; b2_t b = __builtin_convertvector(v, b2_t); return __builtin_bit_cast(unsigned, b); }
; #define PG8_BAR __builtin_amdgcn_s_barrier()
;     __device__ __forceinline__ void operator()(const f32x4 (&acc)[2][2][4][2], const Unit& u, int wr, int wc, int fr, int fq) const {
;     ...
;         for (int ai = 0; ai < 2; ++ai)
; #pragma unroll
;             for (int m = 0; m < 4; ++m) { const int row = row0 + ai * HALF + m * 16; const float rs = rsv[ai][m]; bf16_t* rowp = O + (size_t)row * ldc + col0;
; #pragma unroll
;                 for (int bj = 0; bj < 2; ++bj) { const f32x4 v0 = acc[ai][bj][m][0] * rs, v1 = acc[ai][bj][m][1] * rs;
;                     u32x4 w; w.x = cvt_pk_bf16(v0[0], v0[1]); w.y = cvt_pk_bf16(v0[2], v0[3]); w.z = cvt_pk_bf16(v1[0], v1[1]); w.w = cvt_pk_bf16(v1[2], v1[3]);
;                     *(u32x4*)(rowp + bj * HALF) = w; } }
; template <class Epi, class Sched, bool ALIGN_EPI = false, bool SP2 = false>
; __device__ __forceinline__ void gemm_phase(PG8_LAS unsigned char* lds, const Gemm g, const Sched& S, const Epi& E) {
;     ...
;         if constexpr (!Epi::AFTER_DRAIN) { E(acc, cur, wr, wc, fr, fq); S.done(cur); }
;         if (!has_next) break;
; #pragma unroll
;         for (int a = 0; a < 2; ++a)
; #pragma unroll
;             for (int b = 0; b < 2; ++b)
; #pragma unroll
;                 for (int m = 0; m < 4; ++m)
; #pragma unroll
;                     for (int n = 0; n < 2; ++n) acc[a][b][m][n] = (f32x4){0.f, 0.f, 0.f, 0.f};
;         cur = nxt; cA = nA; cB = nB; ++ui;
;         if constexpr (ALIGN_EPI) { if (wr == 1) PG8_BAR; }
;     }
	v_pk_mul_f32 v[104:105], v[116:117], v[168:169] op_sel_hi:[1,0]
	v_pk_mul_f32 v[82:83], v[82:83], v[170:171] op_sel_hi:[1,0]
	v_cvt_pk_bf16_f32 v104, v104, v105
	v_cvt_pk_bf16_f32 v105, v106, v107
	v_cvt_pk_bf16_f32 v106, v108, v109
	v_cvt_pk_bf16_f32 v107, v110, v111
	global_store_dwordx4 v[112:113], v[104:107], off
	v_pk_mul_f32 v[80:81], v[80:81], v[170:171] op_sel_hi:[1,0]
	v_pk_mul_f32 v[48:49], v[48:49], v[160:161] op_sel_hi:[1,0]
	v_pk_mul_f32 v[104:105], v[90:91], v[168:169] op_sel_hi:[1,0]
	v_pk_mul_f32 v[90:91], v[88:89], v[168:169] op_sel_hi:[1,0]
	v_cvt_pk_bf16_f32 v88, v96, v97
	v_cvt_pk_bf16_f32 v89, v98, v99
	v_cvt_pk_bf16_f32 v90, v90, v91
	v_cvt_pk_bf16_f32 v91, v104, v105
	global_store_dwordx4 v[112:113], v[88:91], off offset:256
	v_pk_mul_f32 v[46:47], v[46:47], v[156:157] op_sel_hi:[1,0]
	v_pk_mul_f32 v[44:45], v[44:45], v[156:157] op_sel_hi:[1,0]
	v_mad_i64_i32 v[88:89], s[0:1], v146, s47, v[158:159]
	v_lshl_add_u64 v[96:97], v[88:89], 0, v[150:151]
	v_pk_mul_f32 v[90:91], v[102:103], v[170:171] op_sel_hi:[1,0]
	v_pk_mul_f32 v[88:89], v[100:101], v[170:171] op_sel_hi:[1,0]
	v_pk_mul_f32 v[34:35], v[34:35], v[156:157] op_sel_hi:[1,0]
	v_cvt_pk_bf16_f32 v88, v88, v89
	v_cvt_pk_bf16_f32 v89, v90, v91
	v_cvt_pk_bf16_f32 v90, v92, v93
	v_cvt_pk_bf16_f32 v91, v94, v95
	global_store_dwordx4 v[96:97], v[88:91], off
	v_pk_mul_f32 v[32:33], v[32:33], v[156:157] op_sel_hi:[1,0]
	v_pk_mul_f32 v[30:31], v[30:31], v[154:155] op_sel_hi:[1,0]
	v_pk_mul_f32 v[88:89], v[74:75], v[170:171] op_sel_hi:[1,0]
	v_pk_mul_f32 v[74:75], v[72:73], v[170:171] op_sel_hi:[1,0]
	v_cvt_pk_bf16_f32 v72, v80, v81
	v_cvt_pk_bf16_f32 v73, v82, v83
	v_cvt_pk_bf16_f32 v74, v74, v75
	v_cvt_pk_bf16_f32 v75, v88, v89
	global_store_dwordx4 v[96:97], v[72:75], off offset:256
	v_pk_mul_f32 v[28:29], v[28:29], v[154:155] op_sel_hi:[1,0]
	v_pk_mul_f32 v[18:19], v[18:19], v[154:155] op_sel_hi:[1,0]
	v_mad_i64_i32 v[72:73], s[0:1], v148, s47, v[158:159]
	v_lshl_add_u64 v[80:81], v[72:73], 0, v[150:151]
	v_pk_mul_f32 v[74:75], v[86:87], v[172:173] op_sel_hi:[1,0]
	v_pk_mul_f32 v[72:73], v[84:85], v[172:173] op_sel_hi:[1,0]
	v_pk_mul_f32 v[16:17], v[16:17], v[154:155] op_sel_hi:[1,0]
	v_cvt_pk_bf16_f32 v72, v72, v73
	v_cvt_pk_bf16_f32 v73, v74, v75
	v_cvt_pk_bf16_f32 v74, v76, v77
	v_cvt_pk_bf16_f32 v75, v78, v79
	global_store_dwordx4 v[80:81], v[72:75], off
	v_pk_mul_f32 v[14:15], v[14:15], v[152:153] op_sel_hi:[1,0]
	v_pk_mul_f32 v[12:13], v[12:13], v[152:153] op_sel_hi:[1,0]
	v_pk_mul_f32 v[72:73], v[66:67], v[172:173] op_sel_hi:[1,0]
	v_pk_mul_f32 v[66:67], v[64:65], v[172:173] op_sel_hi:[1,0]
	v_cvt_pk_bf16_f32 v64, v68, v69
	v_cvt_pk_bf16_f32 v65, v70, v71
	v_cvt_pk_bf16_f32 v66, v66, v67
	v_cvt_pk_bf16_f32 v67, v72, v73
	global_store_dwordx4 v[80:81], v[64:67], off offset:256
	v_pk_mul_f32 v[6:7], v[6:7], v[152:153] op_sel_hi:[1,0]
	v_pk_mul_f32 v[4:5], v[4:5], v[152:153] op_sel_hi:[1,0]
	v_mad_i64_i32 v[64:65], s[0:1], v145, s47, v[158:159]
	v_pk_mul_f32 v[66:67], v[58:59], v[160:161] op_sel_hi:[1,0]
	v_pk_mul_f32 v[58:59], v[56:57], v[160:161] op_sel_hi:[1,0]
	v_lshl_add_u64 v[64:65], v[64:65], 0, v[150:151]
	v_cvt_pk_bf16_f32 v56, v60, v61
	v_cvt_pk_bf16_f32 v57, v62, v63
	v_cvt_pk_bf16_f32 v58, v58, v59
	v_cvt_pk_bf16_f32 v59, v66, v67
	global_store_dwordx4 v[64:65], v[56:59], off
	s_andn2_b64 vcc, exec, s[6:7]
	s_nop 0
	v_pk_mul_f32 v[56:57], v[42:43], v[160:161] op_sel_hi:[1,0]
	v_pk_mul_f32 v[42:43], v[40:41], v[160:161] op_sel_hi:[1,0]
	v_cvt_pk_bf16_f32 v40, v48, v49
	v_cvt_pk_bf16_f32 v41, v50, v51
	v_cvt_pk_bf16_f32 v42, v42, v43
	v_cvt_pk_bf16_f32 v43, v56, v57
	global_store_dwordx4 v[64:65], v[40:43], off offset:256
	s_nop 1
	v_mad_i64_i32 v[40:41], s[0:1], v147, s47, v[158:159]
	v_lshl_add_u64 v[48:49], v[40:41], 0, v[150:151]
	v_pk_mul_f32 v[42:43], v[54:55], v[156:157] op_sel_hi:[1,0]
	v_pk_mul_f32 v[40:41], v[52:53], v[156:157] op_sel_hi:[1,0]
	s_nop 0
	v_cvt_pk_bf16_f32 v40, v40, v41
	v_cvt_pk_bf16_f32 v41, v42, v43
	v_cvt_pk_bf16_f32 v42, v44, v45
	v_cvt_pk_bf16_f32 v43, v46, v47
	global_store_dwordx4 v[48:49], v[40:43], off
	s_nop 1
	v_pk_mul_f32 v[40:41], v[26:27], v[156:157] op_sel_hi:[1,0]
	v_pk_mul_f32 v[26:27], v[24:25], v[156:157] op_sel_hi:[1,0]
	v_cvt_pk_bf16_f32 v24, v32, v33
	v_cvt_pk_bf16_f32 v25, v34, v35
	v_cvt_pk_bf16_f32 v26, v26, v27
	v_cvt_pk_bf16_f32 v27, v40, v41
	global_store_dwordx4 v[48:49], v[24:27], off offset:256
	s_nop 1
	v_mad_i64_i32 v[24:25], s[0:1], v149, s47, v[158:159]
	v_lshl_add_u64 v[32:33], v[24:25], 0, v[150:151]
	v_pk_mul_f32 v[26:27], v[38:39], v[154:155] op_sel_hi:[1,0]
	v_pk_mul_f32 v[24:25], v[36:37], v[154:155] op_sel_hi:[1,0]
	s_nop 0
	v_cvt_pk_bf16_f32 v24, v24, v25
	v_cvt_pk_bf16_f32 v25, v26, v27
	v_cvt_pk_bf16_f32 v26, v28, v29
	v_cvt_pk_bf16_f32 v27, v30, v31
	global_store_dwordx4 v[32:33], v[24:27], off
	s_nop 1
	v_pk_mul_f32 v[24:25], v[10:11], v[154:155] op_sel_hi:[1,0]
	v_pk_mul_f32 v[10:11], v[8:9], v[154:155] op_sel_hi:[1,0]
	v_cvt_pk_bf16_f32 v8, v16, v17
	v_cvt_pk_bf16_f32 v9, v18, v19
	v_cvt_pk_bf16_f32 v10, v10, v11
	v_cvt_pk_bf16_f32 v11, v24, v25
	global_store_dwordx4 v[32:33], v[8:11], off offset:256
	s_nop 1
	v_mad_i64_i32 v[8:9], s[0:1], v169, s47, v[158:159]
	v_lshl_add_u64 v[16:17], v[8:9], 0, v[150:151]
	v_pk_mul_f32 v[10:11], v[22:23], v[152:153] op_sel_hi:[1,0]
	v_pk_mul_f32 v[8:9], v[20:21], v[152:153] op_sel_hi:[1,0]
	s_mov_b64 s[0:1], -1
	v_cvt_pk_bf16_f32 v8, v8, v9
	v_cvt_pk_bf16_f32 v9, v10, v11
	v_cvt_pk_bf16_f32 v10, v12, v13
	v_cvt_pk_bf16_f32 v11, v14, v15
	global_store_dwordx4 v[16:17], v[8:11], off
	s_nop 1
	v_pk_mul_f32 v[8:9], v[2:3], v[152:153] op_sel_hi:[1,0]
	v_pk_mul_f32 v[2:3], v[0:1], v[152:153] op_sel_hi:[1,0]
	v_cvt_pk_bf16_f32 v0, v4, v5
	v_cvt_pk_bf16_f32 v1, v6, v7
	v_cvt_pk_bf16_f32 v2, v2, v3
	v_cvt_pk_bf16_f32 v3, v8, v9
	global_store_dwordx4 v[16:17], v[0:3], off offset:256
	s_cbranch_vccnz .LBB0_911
	s_andn2_b64 vcc, exec, s[14:15]
	s_cbranch_vccnz .LBB0_910
	s_barrier
	s_branch .LBB0_910

; __global__ void __launch_bounds__(512, 2) fwd_megakernel(Ptrs Punused) {
	.amdhsa_kernel _Z14fwd_megakernel4Ptrs
		.amdhsa_group_segment_fixed_size 0
		.amdhsa_private_segment_fixed_size 0
		.amdhsa_kernarg_size 416
		.amdhsa_user_sgpr_count 2
		.amdhsa_user_sgpr_dispatch_ptr 0
		.amdhsa_user_sgpr_queue_ptr 0
		.amdhsa_user_sgpr_kernarg_segment_ptr 1
		.amdhsa_user_sgpr_dispatch_id 0
		.amdhsa_user_sgpr_kernarg_preload_length 0
		.amdhsa_user_sgpr_kernarg_preload_offset 0
		.amdhsa_user_sgpr_private_segment_size 0
		.amdhsa_uses_dynamic_stack 0
		.amdhsa_enable_private_segment 0
		.amdhsa_system_sgpr_workgroup_id_x 1
		.amdhsa_system_sgpr_workgroup_id_y 0
		.amdhsa_system_sgpr_workgroup_id_z 0
		.amdhsa_system_sgpr_workgroup_info 0
		.amdhsa_system_vgpr_workitem_id 2
		.amdhsa_next_free_vgpr 256
		.amdhsa_next_free_sgpr 98
		.amdhsa_accum_offset 256
		.amdhsa_reserve_vcc 1
		.amdhsa_float_round_mode_32 0
		.amdhsa_float_round_mode_16_64 0
		.amdhsa_float_denorm_mode_32 3
		.amdhsa_float_denorm_mode_16_64 3
		.amdhsa_dx10_clamp 1
		.amdhsa_ieee_mode 1
		.amdhsa_fp16_overflow 0
		.amdhsa_tg_split 0
		.amdhsa_exception_fp_ieee_invalid_op 0
		.amdhsa_exception_fp_denorm_src 0
		.amdhsa_exception_fp_ieee_div_zero 0
		.amdhsa_exception_fp_ieee_overflow 0
		.amdhsa_exception_fp_ieee_underflow 0
		.amdhsa_exception_fp_ieee_inexact 0
		.amdhsa_exception_int_div_zero 0
	.end_amdhsa_kernel

; __global__ void __launch_bounds__(512, 2) fwd_megakernel(Ptrs Punused) {
amdhsa.kernels:
  - .agpr_count:     0
    .args:
      - .offset:         0
        .size:           160
        .value_kind:     by_value
      - .offset:         160
        .size:           4
        .value_kind:     hidden_block_count_x
      - .offset:         164
        .size:           4
        .value_kind:     hidden_block_count_y
      - .offset:         168
        .size:           4
        .value_kind:     hidden_block_count_z
      - .offset:         172
        .size:           2
        .value_kind:     hidden_group_size_x
      - .offset:         174
        .size:           2
        .value_kind:     hidden_group_size_y
      - .offset:         176
        .size:           2
        .value_kind:     hidden_group_size_z
      - .offset:         178
        .size:           2
        .value_kind:     hidden_remainder_x
      - .offset:         180
        .size:           2
        .value_kind:     hidden_remainder_y
      - .offset:         182
        .size:           2
        .value_kind:     hidden_remainder_z
      - .offset:         200
        .size:           8
        .value_kind:     hidden_global_offset_x
      - .offset:         208
        .size:           8
        .value_kind:     hidden_global_offset_y
      - .offset:         216
        .size:           8
        .value_kind:     hidden_global_offset_z
      - .offset:         224
        .size:           2
        .value_kind:     hidden_grid_dims
      - .offset:         248
        .size:           8
        .value_kind:     hidden_multigrid_sync_arg
      - .offset:         280
        .size:           4
        .value_kind:     hidden_dynamic_lds_size
    .group_segment_fixed_size: 0
    .kernarg_segment_align: 8
    .kernarg_segment_size: 416
    .language:       OpenCL C
    .language_version:
      - 2
      - 0
    .max_flat_workgroup_size: 512
    .name:           _Z14fwd_megakernel4Ptrs
    .private_segment_fixed_size: 0
    .sgpr_count:     104
    .sgpr_spill_count: 79
    .symbol:         _Z14fwd_megakernel4Ptrs.kd
    .uniform_work_group_size: 1
    .uses_dynamic_stack: false
    .vgpr_count:     256
    .vgpr_spill_count: 0
    .wavefront_size: 64
